# adds accumulator zeroing at the unit heads with 64-bit moves (half the instructions)
# speedup vs baseline: 1.0032x; 1.0032x over previous
; template <class Epi, class Sched, bool ALIGN_EPI = false, bool SP2 = false>
; __device__ __forceinline__ void gemm_phase(PG8_LAS unsigned char* lds, const Gemm g, const Sched& S, const Epi& E) {
;     ...
;         const bool has_next = S.next(ui + 1, nxt);
;         const char* nA = has_next ? (const char*)g.A + (size_t)nxt.pm * tstepA + (size_t)nxt.z * g.azs + (size_t)(nxt.k0 >> 6) * kstA : cA; const char* nB = has_next ? (const char*)g.Bt + (size_t)nxt.pn * tstepB + (size_t)nxt.z * g.bzs + (size_t)nxt.k0 * 2 : cB;
;     ...
; #pragma unroll
;         for (int a = 0; a < 2; ++a)
; #pragma unroll
;             for (int b = 0; b < 2; ++b)
; #pragma unroll
;                 for (int m = 0; m < 4; ++m)
; #pragma unroll
;                     for (int n = 0; n < 2; ++n) acc[a][b][m][n] = (f32x4){0.f, 0.f, 0.f, 0.f};
;         cur = nxt; cA = nA; cB = nB; ++ui;
.LBB0_299:
	s_ashr_i32 s43, s42, 31
	s_lshl_b64 s[4:5], s[42:43], 20
	v_readlane_b32 s12, v254, 41
	v_readlane_b32 s13, v254, 42
	s_add_u32 s46, s12, s4
	s_addc_u32 s47, s13, s5
	s_and_b64 s[4:5], s[34:35], exec
	s_cselect_b32 s4, s47, s51
	s_cselect_b32 s5, s46, s50
	s_ashr_i32 s41, s40, 31
	s_lshl_b64 s[12:13], s[40:41], 20
	v_readlane_b32 s14, v253, 24
	s_add_u32 s48, s14, s12
	v_readlane_b32 s12, v253, 25
	s_addc_u32 s49, s12, s13
	s_and_b64 s[12:13], s[34:35], exec
	s_cselect_b32 s12, s49, s57
	s_cselect_b32 s13, s48, s56
	s_add_u32 s50, s50, 0x80080
	s_addc_u32 s51, s51, 0
	s_add_u32 s41, s56, 0x100
	v_mov_b32_e32 v0, 0
	s_addc_u32 s43, s57, 0
	s_mov_b32 s61, -2
	v_mov_b32_e32 v1, v0
	v_mov_b64_e32 v[2:3], 0
	v_mov_b64_e32 v[4:5], 0
	v_mov_b64_e32 v[6:7], 0
	v_mov_b64_e32 v[16:17], 0
	v_mov_b64_e32 v[18:19], 0
	v_mov_b64_e32 v[20:21], 0
	v_mov_b64_e32 v[22:23], 0
	v_mov_b64_e32 v[32:33], 0
	v_mov_b64_e32 v[34:35], 0
	v_mov_b64_e32 v[36:37], 0
	v_mov_b64_e32 v[38:39], 0
	v_mov_b64_e32 v[48:49], 0
	v_mov_b64_e32 v[50:51], 0
	v_mov_b64_e32 v[52:53], 0
	v_mov_b64_e32 v[54:55], 0
	v_mov_b64_e32 v[8:9], 0
	v_mov_b64_e32 v[10:11], 0
	v_mov_b64_e32 v[12:13], 0
	v_mov_b64_e32 v[14:15], 0
	v_mov_b64_e32 v[24:25], 0
	v_mov_b64_e32 v[26:27], 0
	v_mov_b64_e32 v[28:29], 0
	v_mov_b64_e32 v[30:31], 0
	v_mov_b64_e32 v[40:41], 0
	v_mov_b64_e32 v[42:43], 0
	v_mov_b64_e32 v[44:45], 0
	v_mov_b64_e32 v[46:47], 0
	v_mov_b64_e32 v[56:57], 0
	v_mov_b64_e32 v[58:59], 0
	v_mov_b64_e32 v[60:61], 0
	v_mov_b64_e32 v[62:63], 0
	v_mov_b64_e32 v[64:65], 0
	v_mov_b64_e32 v[66:67], 0
	v_mov_b64_e32 v[68:69], 0
	v_mov_b64_e32 v[70:71], 0
	v_mov_b64_e32 v[80:81], 0
	v_mov_b64_e32 v[82:83], 0
	v_mov_b64_e32 v[84:85], 0
	v_mov_b64_e32 v[86:87], 0
	v_mov_b64_e32 v[96:97], 0
	v_mov_b64_e32 v[98:99], 0
	v_mov_b64_e32 v[100:101], 0
	v_mov_b64_e32 v[102:103], 0
	v_mov_b64_e32 v[112:113], 0
	v_mov_b64_e32 v[114:115], 0
	v_mov_b64_e32 v[116:117], 0
	v_mov_b64_e32 v[118:119], 0
	v_mov_b64_e32 v[72:73], 0
	v_mov_b64_e32 v[74:75], 0
	v_mov_b64_e32 v[76:77], 0
	v_mov_b64_e32 v[78:79], 0
	v_mov_b64_e32 v[88:89], 0
	v_mov_b64_e32 v[90:91], 0
	v_mov_b64_e32 v[92:93], 0
	v_mov_b64_e32 v[94:95], 0
	v_mov_b64_e32 v[104:105], 0
	v_mov_b64_e32 v[106:107], 0
	v_mov_b64_e32 v[108:109], 0
	v_mov_b64_e32 v[110:111], 0
	v_mov_b64_e32 v[120:121], 0
	v_mov_b64_e32 v[122:123], 0
	v_mov_b64_e32 v[124:125], 0
	v_mov_b64_e32 v[126:127], 0

; #define PG8_STAGE(bufoff, gbase, voff) do { _Pragma("unroll") for (int _i = 0; _i < 2; ++_i) \
;         __builtin_amdgcn_global_load_lds((const unsigned*)((const char*)(gbase) + (voff)[_i]), (PG8_LAS unsigned*)(lds + (bufoff) + ldsw + _i * 8192), 16, 0, 0); } while (0)
; #define PG8_WAIT_V(n) asm volatile("s_waitcnt vmcnt(" #n ")" ::: "memory")
; #define PG8_BAR __builtin_amdgcn_s_barrier()
; template <class Epi, class Sched, bool ALIGN_EPI = false, bool SP2 = false>
; __device__ __forceinline__ void gemm_phase(PG8_LAS unsigned char* lds, const Gemm g, const Sched& S, const Epi& E) {
;     ...
;     const int aoff = lds_byte(wr * 64 + fr, fq * 8), boff = lds_byte(wc * 32 + fr, fq * 8);
;     ...
;     Unit cur, nxt; int ui = 0;
;     if (!S.next(0, cur)) return;
;     f32x4 acc[2][2][4][2];
; #pragma unroll
;     for (int a = 0; a < 2; ++a)
; #pragma unroll
;         for (int b = 0; b < 2; ++b)
; #pragma unroll
;             for (int m = 0; m < 4; ++m)
; #pragma unroll
;                 for (int n = 0; n < 2; ++n) acc[a][b][m][n] = (f32x4){0.f, 0.f, 0.f, 0.f};
;     bf16x8 At[4][2], B0[2][2], B1[2][2];
;     const char* cA = (const char*)g.A + (size_t)cur.pm * tstepA + (size_t)cur.z * g.azs + (size_t)(cur.k0 >> 6) * kstA; const char* cB = (const char*)g.Bt + (size_t)cur.pn * tstepB + (size_t)cur.z * g.bzs + (size_t)cur.k0 * 2;
;     S.a_ready(cur);
;     if constexpr (SP2) {
;         PG8_STAGE(PG8_SB(0, 0), cB, voffB); PG8_STAGE(PG8_SB(0, 1), cB + hstepB, voffB); PG8_STAGE(PG8_SA(0, 0), cA, voffA); PG8_STAGE(PG8_SA(0, 1), cA + hstepA, voffA);
;         if (wr == 1) PG8_BAR;
;         PG8_WAIT_V(2); PG8_BAR;
;         PG8_STAGE(PG8_SB(1, 0), cB + kstep, voffB); PG8_STAGE(PG8_SA(1, 0), cA + kstA, voffA); PG8_STAGE(PG8_SB(1, 1), cB + hstepB + kstep, voffB);
;         PG8_WAIT_V(6); PG8_BAR;
.LBB0_375:
	v_lshrrev_b32_e32 v7, 1, v4
	v_and_b32_e32 v8, 24, v7
	v_and_b32_e32 v5, 15, v4
	v_lshlrev_b32_e32 v7, 1, v8
	v_lshlrev_b32_e32 v4, 2, v4
	v_lshl_or_b32 v6, s0, 6, v5
	v_lshl_or_b32 v5, v5, 6, v7
	s_lshl_b32 s0, s0, 13
	v_and_b32_e32 v4, 32, v4
	v_bitop3_b32 v9, v5, s0, v4 bitop3:0xde
	s_lshl_b32 s0, s1, 5
	s_and_b32 s4, s0, 0x60
	s_lshl_b32 s0, s4, 7
	v_bitop3_b32 v177, v5, s0, v4 bitop3:0xde
	v_readlane_b32 s0, v254, 34
	v_readlane_b32 s1, v254, 35
	s_add_u32 s3, s0, 0x104000
	s_mov_b64 s[54:55], 0x80
	s_addc_u32 s44, s1, 0
	s_add_i32 m0, s66, 0x18000
	v_lshl_add_u64 v[2:3], v[2:3], 0, s[54:55]
	s_waitcnt vmcnt(2)
	s_barrier
	global_load_lds_dwordx4 v[2:3], off
	s_add_i32 m0, s66, 0x1a000
	s_add_u32 s0, s38, 0x8000
	v_lshl_add_u64 v[0:1], v[0:1], 0, s[54:55]
	s_addc_u32 s1, s39, 0
	s_add_i32 s45, s66, 0x8000
	global_load_lds_dwordx4 v[0:1], off
	v_lshl_add_u64 v[0:1], s[0:1], 0, v[128:129]
	s_mov_b32 m0, s45
	s_add_i32 s56, s66, 0xa000
	global_load_lds_dwordx4 v[0:1], off
	v_lshl_add_u64 v[0:1], s[0:1], 0, v[132:133]
	s_add_u32 s0, s40, 0x160080
	s_mov_b32 m0, s56
	s_addc_u32 s1, s41, 0
	global_load_lds_dwordx4 v[0:1], off
	s_add_i32 m0, s66, 0x1c000
	v_lshl_add_u64 v[0:1], s[0:1], 0, v[130:131]
	global_load_lds_dwordx4 v[0:1], off
	v_lshl_add_u64 v[0:1], s[0:1], 0, v[134:135]
	s_add_i32 m0, s66, 0x1e000
	v_ashrrev_i32_e32 v7, 31, v6
	global_load_lds_dwordx4 v[0:1], off
	v_or_b32_e32 v0, 16, v6
	v_lshlrev_b64 v[136:137], 13, v[6:7]
	v_ashrrev_i32_e32 v1, 31, v0
	s_mov_b64 s[0:1], 0x100000
	v_lshlrev_b64 v[138:139], 13, v[0:1]
	v_or_b32_e32 v0, 32, v6
	v_lshl_add_u64 v[144:145], v[136:137], 0, s[0:1]
	s_mov_b64 s[0:1], 0x120000
	v_ashrrev_i32_e32 v1, 31, v0
	v_lshl_add_u64 v[146:147], v[136:137], 0, s[0:1]
	s_mov_b64 s[0:1], 0x140000
	v_lshlrev_b64 v[140:141], 13, v[0:1]
	v_or_b32_e32 v0, 48, v6
	v_lshl_add_u64 v[148:149], v[136:137], 0, s[0:1]
	s_mov_b64 s[0:1], 0x160000
	s_waitcnt vmcnt(6)
	v_ashrrev_i32_e32 v1, 31, v0
	v_lshl_add_u64 v[150:151], v[136:137], 0, s[0:1]
	v_readlane_b32 s0, v255, 12
	s_cmpk_lt_u32 s10, 0x100
	v_lshlrev_b64 v[142:143], 13, v[0:1]
	v_lshlrev_b64 v[0:1], 12, v[6:7]
	v_readlane_b32 s1, v255, 13
	s_cselect_b64 s[70:71], -1, 0
	v_or_b32_e32 v178, s4, v8
	v_lshl_add_u64 v[152:153], s[0:1], 0, v[0:1]
	s_movk_i32 s57, 0x58
	v_mov_b64_e32 v[154:155], 0x1ff
	s_add_i32 s10, 0, 0x10000
	s_add_i32 s11, 0, 0x14000
	v_add_u32_e32 v179, 0, v9
	v_mov_b64_e32 v[156:157], 0x1e8481
	s_mov_b32 s33, 0
	s_mov_b32 s85, 0
	v_mov_b64_e32 v[0:1], 0
	v_mov_b64_e32 v[2:3], 0
	v_mov_b64_e32 v[4:5], 0
	v_mov_b64_e32 v[6:7], 0
	v_mov_b64_e32 v[8:9], 0
	v_mov_b64_e32 v[10:11], 0
	v_mov_b64_e32 v[12:13], 0
	v_mov_b64_e32 v[14:15], 0
	v_mov_b64_e32 v[16:17], 0
	v_mov_b64_e32 v[18:19], 0
	v_mov_b64_e32 v[20:21], 0
	v_mov_b64_e32 v[22:23], 0
	v_mov_b64_e32 v[24:25], 0
	v_mov_b64_e32 v[26:27], 0
	v_mov_b64_e32 v[28:29], 0
	v_mov_b64_e32 v[30:31], 0
	v_mov_b64_e32 v[32:33], 0
	v_mov_b64_e32 v[34:35], 0
	v_mov_b64_e32 v[36:37], 0
	v_mov_b64_e32 v[38:39], 0
	v_mov_b64_e32 v[40:41], 0
	v_mov_b64_e32 v[42:43], 0
	v_mov_b64_e32 v[44:45], 0
	v_mov_b64_e32 v[46:47], 0
	v_mov_b64_e32 v[48:49], 0
	v_mov_b64_e32 v[50:51], 0
	v_mov_b64_e32 v[52:53], 0
	v_mov_b64_e32 v[54:55], 0
	v_mov_b64_e32 v[56:57], 0
	v_mov_b64_e32 v[58:59], 0
	v_mov_b64_e32 v[60:61], 0
	v_mov_b64_e32 v[62:63], 0
	v_mov_b64_e32 v[64:65], 0
	v_mov_b64_e32 v[66:67], 0
	v_mov_b64_e32 v[68:69], 0
	v_mov_b64_e32 v[70:71], 0
	v_mov_b64_e32 v[72:73], 0
	v_mov_b64_e32 v[74:75], 0
	v_mov_b64_e32 v[76:77], 0
	v_mov_b64_e32 v[78:79], 0
	v_mov_b64_e32 v[80:81], 0
	v_mov_b64_e32 v[82:83], 0
	v_mov_b64_e32 v[84:85], 0
	v_mov_b64_e32 v[86:87], 0
	v_mov_b64_e32 v[88:89], 0
	v_mov_b64_e32 v[90:91], 0
	v_mov_b64_e32 v[92:93], 0
	v_mov_b64_e32 v[94:95], 0
	v_mov_b64_e32 v[96:97], 0
	v_mov_b64_e32 v[98:99], 0
	v_mov_b64_e32 v[100:101], 0
	v_mov_b64_e32 v[102:103], 0
	v_mov_b64_e32 v[104:105], 0
	v_mov_b64_e32 v[106:107], 0
	v_mov_b64_e32 v[108:109], 0
	v_mov_b64_e32 v[110:111], 0
	v_mov_b64_e32 v[112:113], 0
	v_mov_b64_e32 v[114:115], 0
	v_mov_b64_e32 v[116:117], 0
	v_mov_b64_e32 v[118:119], 0
	v_mov_b64_e32 v[120:121], 0
	v_mov_b64_e32 v[122:123], 0
	v_mov_b64_e32 v[124:125], 0
	v_mov_b64_e32 v[126:127], 0
	s_barrier
	s_branch .LBB0_378
.LBB0_376:
	v_mov_b32_e32 v0, 0
	s_mov_b32 s57, s68
	s_mov_b32 s33, s86
	s_mov_b32 s8, s87
	s_mov_b32 s34, s84
	s_mov_b64 s[40:41], s[62:63]
	s_mov_b64 s[38:39], s[60:61]
	s_mov_b32 s85, s69
	v_mov_b32_e32 v1, v0
	v_mov_b64_e32 v[2:3], 0
	v_mov_b64_e32 v[4:5], 0
	v_mov_b64_e32 v[6:7], 0
	v_mov_b64_e32 v[8:9], 0
	v_mov_b64_e32 v[10:11], 0
	v_mov_b64_e32 v[12:13], 0
	v_mov_b64_e32 v[14:15], 0
	v_mov_b64_e32 v[16:17], 0
	v_mov_b64_e32 v[18:19], 0
	v_mov_b64_e32 v[20:21], 0
	v_mov_b64_e32 v[22:23], 0
	v_mov_b64_e32 v[24:25], 0
	v_mov_b64_e32 v[26:27], 0
	v_mov_b64_e32 v[28:29], 0
	v_mov_b64_e32 v[30:31], 0
	v_mov_b64_e32 v[32:33], 0
	v_mov_b64_e32 v[34:35], 0
	v_mov_b64_e32 v[36:37], 0
	v_mov_b64_e32 v[38:39], 0
	v_mov_b64_e32 v[40:41], 0
	v_mov_b64_e32 v[42:43], 0
	v_mov_b64_e32 v[44:45], 0
	v_mov_b64_e32 v[46:47], 0
	v_mov_b64_e32 v[48:49], 0
	v_mov_b64_e32 v[50:51], 0
	v_mov_b64_e32 v[52:53], 0
	v_mov_b64_e32 v[54:55], 0
	v_mov_b64_e32 v[56:57], 0
	v_mov_b64_e32 v[58:59], 0
	v_mov_b64_e32 v[60:61], 0
	v_mov_b64_e32 v[62:63], 0
	v_mov_b64_e32 v[64:65], 0
	v_mov_b64_e32 v[66:67], 0
	v_mov_b64_e32 v[68:69], 0
	v_mov_b64_e32 v[70:71], 0
	v_mov_b64_e32 v[72:73], 0
	v_mov_b64_e32 v[74:75], 0
	v_mov_b64_e32 v[76:77], 0
	v_mov_b64_e32 v[78:79], 0
	v_mov_b64_e32 v[80:81], 0
	v_mov_b64_e32 v[82:83], 0
	v_mov_b64_e32 v[84:85], 0
	v_mov_b64_e32 v[86:87], 0
	v_mov_b64_e32 v[88:89], 0
	v_mov_b64_e32 v[90:91], 0
	v_mov_b64_e32 v[92:93], 0
	v_mov_b64_e32 v[94:95], 0
	v_mov_b64_e32 v[96:97], 0
	v_mov_b64_e32 v[98:99], 0
	v_mov_b64_e32 v[100:101], 0
	v_mov_b64_e32 v[102:103], 0
	v_mov_b64_e32 v[104:105], 0
	v_mov_b64_e32 v[106:107], 0
	v_mov_b64_e32 v[108:109], 0
	v_mov_b64_e32 v[110:111], 0
	v_mov_b64_e32 v[112:113], 0
	v_mov_b64_e32 v[114:115], 0
	v_mov_b64_e32 v[116:117], 0
	v_mov_b64_e32 v[118:119], 0
	v_mov_b64_e32 v[120:121], 0
	v_mov_b64_e32 v[122:123], 0
	v_mov_b64_e32 v[124:125], 0
	v_mov_b64_e32 v[126:127], 0

; template <class Epi, class Sched, bool ALIGN_EPI = false, bool SP2 = false>
; __device__ __forceinline__ void gemm_phase(PG8_LAS unsigned char* lds, const Gemm g, const Sched& S, const Epi& E) {
;     ...
; #pragma unroll
;         for (int a = 0; a < 2; ++a)
; #pragma unroll
;             for (int b = 0; b < 2; ++b)
; #pragma unroll
;                 for (int m = 0; m < 4; ++m)
; #pragma unroll
;                     for (int n = 0; n < 2; ++n) acc[a][b][m][n] = (f32x4){0.f, 0.f, 0.f, 0.f};
;         cur = nxt; cA = nA; cB = nB; ++ui;
.LBB0_655:
	s_add_u32 s50, s50, 0x80080
	s_addc_u32 s51, s51, 0
	s_add_u32 s4, s52, 0x100
	v_mov_b32_e32 v0, 0
	s_addc_u32 s5, s53, 0
	s_mov_b32 s46, -2
	v_mov_b32_e32 v1, v0
	v_mov_b64_e32 v[2:3], 0
	v_mov_b64_e32 v[4:5], 0
	v_mov_b64_e32 v[6:7], 0
	v_mov_b64_e32 v[12:13], 0
	v_mov_b64_e32 v[14:15], 0
	v_mov_b64_e32 v[20:21], 0
	v_mov_b64_e32 v[22:23], 0
	v_mov_b64_e32 v[28:29], 0
	v_mov_b64_e32 v[30:31], 0
	v_mov_b64_e32 v[36:37], 0
	v_mov_b64_e32 v[38:39], 0
	v_mov_b64_e32 v[44:45], 0
	v_mov_b64_e32 v[46:47], 0
	v_mov_b64_e32 v[52:53], 0
	v_mov_b64_e32 v[54:55], 0
	v_mov_b64_e32 v[8:9], 0
	v_mov_b64_e32 v[10:11], 0
	v_mov_b64_e32 v[16:17], 0
	v_mov_b64_e32 v[18:19], 0
	v_mov_b64_e32 v[24:25], 0
	v_mov_b64_e32 v[26:27], 0
	v_mov_b64_e32 v[32:33], 0
	v_mov_b64_e32 v[34:35], 0
	v_mov_b64_e32 v[40:41], 0
	v_mov_b64_e32 v[42:43], 0
	v_mov_b64_e32 v[48:49], 0
	v_mov_b64_e32 v[50:51], 0
	v_mov_b64_e32 v[56:57], 0
	v_mov_b64_e32 v[58:59], 0
	v_mov_b64_e32 v[60:61], 0
	v_mov_b64_e32 v[62:63], 0
	v_mov_b64_e32 v[64:65], 0
	v_mov_b64_e32 v[66:67], 0
	v_mov_b64_e32 v[68:69], 0
	v_mov_b64_e32 v[70:71], 0
	v_mov_b64_e32 v[76:77], 0
	v_mov_b64_e32 v[78:79], 0
	v_mov_b64_e32 v[84:85], 0
	v_mov_b64_e32 v[86:87], 0
	v_mov_b64_e32 v[92:93], 0
	v_mov_b64_e32 v[94:95], 0
	v_mov_b64_e32 v[100:101], 0
	v_mov_b64_e32 v[102:103], 0
	v_mov_b64_e32 v[108:109], 0
	v_mov_b64_e32 v[110:111], 0
	v_mov_b64_e32 v[116:117], 0
	v_mov_b64_e32 v[118:119], 0
	v_mov_b64_e32 v[72:73], 0
	v_mov_b64_e32 v[74:75], 0
	v_mov_b64_e32 v[80:81], 0
	v_mov_b64_e32 v[82:83], 0
	v_mov_b64_e32 v[88:89], 0
	v_mov_b64_e32 v[90:91], 0
	v_mov_b64_e32 v[96:97], 0
	v_mov_b64_e32 v[98:99], 0
	v_mov_b64_e32 v[104:105], 0
	v_mov_b64_e32 v[106:107], 0
	v_mov_b64_e32 v[112:113], 0
	v_mov_b64_e32 v[114:115], 0
	v_mov_b64_e32 v[120:121], 0
	v_mov_b64_e32 v[122:123], 0
	v_mov_b64_e32 v[124:125], 0
	v_mov_b64_e32 v[126:127], 0

; template <class Epi, class Sched, bool ALIGN_EPI = false, bool SP2 = false>
; __device__ __forceinline__ void gemm_phase(PG8_LAS unsigned char* lds, const Gemm g, const Sched& S, const Epi& E) {
;     ...
;         const char* nA = has_next ? (const char*)g.A + (size_t)nxt.pm * tstepA + (size_t)nxt.z * g.azs + (size_t)(nxt.k0 >> 6) * kstA : cA; const char* nB = has_next ? (const char*)g.Bt + (size_t)nxt.pn * tstepB + (size_t)nxt.z * g.bzs + (size_t)nxt.k0 * 2 : cB;
;     ...
; #pragma unroll
;         for (int a = 0; a < 2; ++a)
; #pragma unroll
;             for (int b = 0; b < 2; ++b)
; #pragma unroll
;                 for (int m = 0; m < 4; ++m)
; #pragma unroll
;                     for (int n = 0; n < 2; ++n) acc[a][b][m][n] = (f32x4){0.f, 0.f, 0.f, 0.f};
;         cur = nxt; cA = nA; cB = nB; ++ui;
.LBB0_928:
	s_ashr_i32 s49, s48, 31
	s_lshl_b64 s[46:47], s[48:49], 20
	s_add_u32 s62, s3, s46
	s_addc_u32 s63, s6, s47
	s_and_b64 s[46:47], s[60:61], exec
	s_cselect_b32 s45, s63, s51
	s_cselect_b32 s46, s62, s50
	s_ashr_i32 s55, s54, 31
	s_lshl_b64 s[56:57], s[54:55], 20
	s_add_u32 s64, s36, s56
	s_addc_u32 s65, s37, s57
	s_and_b64 s[56:57], s[60:61], exec
	s_cselect_b32 s47, s65, s53
	s_cselect_b32 s49, s64, s52
	s_add_u32 s50, s50, 0x80080
	s_addc_u32 s51, s51, 0
	s_add_u32 s55, s52, 0x100
	v_mov_b32_e32 v0, 0
	s_addc_u32 s56, s53, 0
	s_mov_b32 s57, -2
	v_mov_b32_e32 v1, v0
	v_mov_b64_e32 v[2:3], 0
	v_mov_b64_e32 v[4:5], 0
	v_mov_b64_e32 v[6:7], 0
	v_mov_b64_e32 v[16:17], 0
	v_mov_b64_e32 v[18:19], 0
	v_mov_b64_e32 v[20:21], 0
	v_mov_b64_e32 v[22:23], 0
	v_mov_b64_e32 v[32:33], 0
	v_mov_b64_e32 v[34:35], 0
	v_mov_b64_e32 v[36:37], 0
	v_mov_b64_e32 v[38:39], 0
	v_mov_b64_e32 v[48:49], 0
	v_mov_b64_e32 v[50:51], 0
	v_mov_b64_e32 v[52:53], 0
	v_mov_b64_e32 v[54:55], 0
	v_mov_b64_e32 v[8:9], 0
	v_mov_b64_e32 v[10:11], 0
	v_mov_b64_e32 v[12:13], 0
	v_mov_b64_e32 v[14:15], 0
	v_mov_b64_e32 v[24:25], 0
	v_mov_b64_e32 v[26:27], 0
	v_mov_b64_e32 v[28:29], 0
	v_mov_b64_e32 v[30:31], 0
	v_mov_b64_e32 v[40:41], 0
	v_mov_b64_e32 v[42:43], 0
	v_mov_b64_e32 v[44:45], 0
	v_mov_b64_e32 v[46:47], 0
	v_mov_b64_e32 v[56:57], 0
	v_mov_b64_e32 v[58:59], 0
	v_mov_b64_e32 v[60:61], 0
	v_mov_b64_e32 v[62:63], 0
	v_mov_b64_e32 v[64:65], 0
	v_mov_b64_e32 v[66:67], 0
	v_mov_b64_e32 v[68:69], 0
	v_mov_b64_e32 v[70:71], 0
	v_mov_b64_e32 v[80:81], 0
	v_mov_b64_e32 v[82:83], 0
	v_mov_b64_e32 v[84:85], 0
	v_mov_b64_e32 v[86:87], 0
	v_mov_b64_e32 v[96:97], 0
	v_mov_b64_e32 v[98:99], 0
	v_mov_b64_e32 v[100:101], 0
	v_mov_b64_e32 v[102:103], 0
	v_mov_b64_e32 v[112:113], 0
	v_mov_b64_e32 v[114:115], 0
	v_mov_b64_e32 v[116:117], 0
	v_mov_b64_e32 v[118:119], 0
	v_mov_b64_e32 v[72:73], 0
	v_mov_b64_e32 v[74:75], 0
	v_mov_b64_e32 v[76:77], 0
	v_mov_b64_e32 v[78:79], 0
	v_mov_b64_e32 v[88:89], 0
	v_mov_b64_e32 v[90:91], 0
	v_mov_b64_e32 v[92:93], 0
	v_mov_b64_e32 v[94:95], 0
	v_mov_b64_e32 v[104:105], 0
	v_mov_b64_e32 v[106:107], 0
	v_mov_b64_e32 v[108:109], 0
	v_mov_b64_e32 v[110:111], 0
	v_mov_b64_e32 v[120:121], 0
	v_mov_b64_e32 v[122:123], 0
	v_mov_b64_e32 v[124:125], 0
	v_mov_b64_e32 v[126:127], 0

;     __device__ __forceinline__ void operator()(const f32x4 (&acc)[2][2][4][2], const Unit& u, int wr, int wc, int fr, int fq) const {
;     ...
;         const int rloc0 = wr * 64 + fr, col0 = u.pn * BM + wc * 32 + 8 * fq;
;         if (u.z) {
;             float* sp = SLAB + ((size_t)(u.z - 1) * 512 + b * 256) * 2048;
; #pragma unroll
;             for (int ai = 0; ai < 2; ++ai)
; #pragma unroll
;                 for (int m = 0; m < 4; ++m) { float* dp = sp + (size_t)(rloc0 + ai * HALF + m * 16) * 2048 + col0;
; #pragma unroll
;                     for (int bj = 0; bj < 2; ++bj)
; #pragma unroll
;                         for (int n = 0; n < 2; ++n) *(f32x4*)(dp + bj * HALF + 4 * n) = acc[ai][bj][m][n]; }
; template <class Epi, class Sched, bool ALIGN_EPI = false, bool SP2 = false>
; __device__ __forceinline__ void gemm_phase(PG8_LAS unsigned char* lds, const Gemm g, const Sched& S, const Epi& E) {
;     ...
;     f32x4 acc[2][2][4][2];
; #pragma unroll
;     for (int a = 0; a < 2; ++a)
; #pragma unroll
;         for (int b = 0; b < 2; ++b)
; #pragma unroll
;             for (int m = 0; m < 4; ++m)
; #pragma unroll
;                 for (int n = 0; n < 2; ++n) acc[a][b][m][n] = (f32x4){0.f, 0.f, 0.f, 0.f};
;     bf16x8 At[4][2], B0[2][2], B1[2][2];
;     const char* cA = (const char*)g.A + (size_t)cur.pm * tstepA + (size_t)cur.z * g.azs + (size_t)(cur.k0 >> 6) * kstA; const char* cB = (const char*)g.Bt + (size_t)cur.pn * tstepB + (size_t)cur.z * g.bzs + (size_t)cur.k0 * 2;
;     S.a_ready(cur);
;     if constexpr (SP2) {
;         PG8_STAGE(PG8_SB(0, 0), cB, voffB); PG8_STAGE(PG8_SB(0, 1), cB + hstepB, voffB); PG8_STAGE(PG8_SA(0, 0), cA, voffA); PG8_STAGE(PG8_SA(0, 1), cA + hstepA, voffA);
;         if (wr == 1) PG8_BAR;
;         PG8_WAIT_V(2); PG8_BAR;
;         PG8_STAGE(PG8_SB(1, 0), cB + kstep, voffB); PG8_STAGE(PG8_SA(1, 0), cA + kstA, voffA); PG8_STAGE(PG8_SB(1, 1), cB + hstepB + kstep, voffB);
;         PG8_WAIT_V(6); PG8_BAR;
;     } else {
;         PG8_STAGE(PG8_SB(0, 0), cB, voffB); PG8_STAGE(PG8_SA(0, 0), cA, voffA); PG8_STAGE(PG8_SB(0, 1), cB + hstepB, voffB); PG8_STAGE(PG8_SA(0, 1), cA + hstepA, voffA);
;         if (wr == 1) PG8_BAR;
;         PG8_WAIT_V(4); PG8_BAR;
;         PG8_STAGE(PG8_SB(1, 0), cB + kstep, voffB); PG8_STAGE(PG8_SA(1, 0), cA + kstA, voffA); PG8_STAGE(PG8_SB(1, 1), cB + hstepB + kstep, voffB);
;         PG8_WAIT_V(6); PG8_BAR;
;     }
.LBB0_1032:
	v_lshrrev_b32_e32 v11, 1, v8
	v_and_b32_e32 v12, 24, v11
	v_and_b32_e32 v9, 15, v8
	v_lshlrev_b32_e32 v11, 1, v12
	v_lshlrev_b32_e32 v8, 2, v8
	v_lshl_or_b32 v10, s0, 6, v9
	v_lshl_or_b32 v9, v9, 6, v11
	s_lshl_b32 s0, s0, 13
	v_and_b32_e32 v8, 32, v8
	v_bitop3_b32 v13, v9, s0, v8 bitop3:0xde
	s_lshl_b32 s0, s1, 5
	s_and_b32 s5, s0, 0x60
	s_lshl_b32 s0, s5, 7
	v_readlane_b32 s14, v254, 34
	v_readlane_b32 s15, v254, 35
	s_add_u32 s45, s14, 0x10a000
	s_mov_b64 s[70:71], 0x80
	s_addc_u32 s3, s15, 0
	s_add_i32 m0, s21, 0x18000
	v_lshl_add_u64 v[6:7], v[6:7], 0, s[70:71]
	s_lshl_b32 s92, s12, 9
	s_waitcnt vmcnt(2)
	s_barrier
	global_load_lds_dwordx4 v[6:7], off
	v_lshl_add_u64 v[4:5], v[4:5], 0, s[70:71]
	s_add_i32 m0, s21, 0x1a000
	s_add_i32 s56, s21, 0x8000
	s_add_i32 s57, s21, 0xa000
	v_bitop3_b32 v179, v9, s0, v8 bitop3:0xde
	global_load_lds_dwordx4 v[4:5], off
	v_lshl_add_u64 v[0:1], v[0:1], 0, s[70:71]
	s_mov_b32 m0, s56
	s_add_u32 s0, s62, 0x80080
	global_load_lds_dwordx4 v[0:1], off
	v_lshl_add_u64 v[0:1], v[2:3], 0, s[70:71]
	s_mov_b32 m0, s57
	s_addc_u32 s1, s63, 0
	global_load_lds_dwordx4 v[0:1], off
	s_add_i32 m0, s21, 0x1c000
	v_lshl_add_u64 v[0:1], s[0:1], 0, v[146:147]
	global_load_lds_dwordx4 v[0:1], off
	v_lshl_add_u64 v[0:1], s[0:1], 0, v[150:151]
	s_add_i32 m0, s21, 0x1e000
	v_ashrrev_i32_e32 v11, 31, v10
	global_load_lds_dwordx4 v[0:1], off
	v_or_b32_e32 v0, 16, v10
	v_lshlrev_b64 v[152:153], 13, v[10:11]
	v_ashrrev_i32_e32 v1, 31, v0
	s_mov_b64 s[0:1], 0x100000
	v_lshlrev_b64 v[154:155], 13, v[0:1]
	v_or_b32_e32 v0, 32, v10
	v_lshl_add_u64 v[160:161], v[152:153], 0, s[0:1]
	s_mov_b64 s[0:1], 0x120000
	v_ashrrev_i32_e32 v1, 31, v0
	v_lshl_add_u64 v[162:163], v[152:153], 0, s[0:1]
	s_mov_b64 s[0:1], 0x140000
	v_lshlrev_b64 v[156:157], 13, v[0:1]
	v_or_b32_e32 v0, 48, v10
	v_lshl_add_u64 v[164:165], v[152:153], 0, s[0:1]
	s_mov_b64 s[0:1], 0x160000
	s_waitcnt vmcnt(6)
	v_ashrrev_i32_e32 v1, 31, v0
	v_lshl_add_u64 v[166:167], v[152:153], 0, s[0:1]
	v_readlane_b32 s0, v255, 12
	s_cmpk_lt_u32 s4, 0x100
	v_lshlrev_b64 v[158:159], 13, v[0:1]
	v_lshlrev_b64 v[0:1], 12, v[10:11]
	v_readlane_b32 s1, v255, 13
	s_cselect_b64 s[72:73], -1, 0
	v_or_b32_e32 v180, s5, v12
	v_lshl_add_u64 v[168:169], s[0:1], 0, v[0:1]
	v_mov_b64_e32 v[170:171], 0x1ff
	s_add_i32 s10, 0, 0x10000
	s_add_i32 s11, 0, 0x14000
	v_add_u32_e32 v181, 0, v13
	v_mov_b64_e32 v[172:173], 0x1e8481
	s_mov_b32 s33, 0
	s_mov_b32 s86, 0
	v_mov_b64_e32 v[0:1], 0
	v_mov_b64_e32 v[2:3], 0
	v_mov_b64_e32 v[4:5], 0
	v_mov_b64_e32 v[6:7], 0
	v_mov_b64_e32 v[8:9], 0
	v_mov_b64_e32 v[10:11], 0
	v_mov_b64_e32 v[12:13], 0
	v_mov_b64_e32 v[14:15], 0
	v_mov_b64_e32 v[16:17], 0
	v_mov_b64_e32 v[18:19], 0
	v_mov_b64_e32 v[20:21], 0
	v_mov_b64_e32 v[22:23], 0
	v_mov_b64_e32 v[24:25], 0
	v_mov_b64_e32 v[26:27], 0
	v_mov_b64_e32 v[28:29], 0
	v_mov_b64_e32 v[30:31], 0
	v_mov_b64_e32 v[32:33], 0
	v_mov_b64_e32 v[34:35], 0
	v_mov_b64_e32 v[36:37], 0
	v_mov_b64_e32 v[38:39], 0
	v_mov_b64_e32 v[40:41], 0
	v_mov_b64_e32 v[42:43], 0
	v_mov_b64_e32 v[44:45], 0
	v_mov_b64_e32 v[46:47], 0
	v_mov_b64_e32 v[48:49], 0
	v_mov_b64_e32 v[50:51], 0
	v_mov_b64_e32 v[52:53], 0
	v_mov_b64_e32 v[54:55], 0
	v_mov_b64_e32 v[56:57], 0
	v_mov_b64_e32 v[58:59], 0
	v_mov_b64_e32 v[60:61], 0
	v_mov_b64_e32 v[62:63], 0
	v_mov_b64_e32 v[64:65], 0
	v_mov_b64_e32 v[66:67], 0
	v_mov_b64_e32 v[68:69], 0
	v_mov_b64_e32 v[70:71], 0
	v_mov_b64_e32 v[72:73], 0
	v_mov_b64_e32 v[74:75], 0
	v_mov_b64_e32 v[76:77], 0
	v_mov_b64_e32 v[78:79], 0
	v_mov_b64_e32 v[80:81], 0
	v_mov_b64_e32 v[82:83], 0
	v_mov_b64_e32 v[84:85], 0
	v_mov_b64_e32 v[86:87], 0
	v_mov_b64_e32 v[88:89], 0
	v_mov_b64_e32 v[90:91], 0
	v_mov_b64_e32 v[92:93], 0
	v_mov_b64_e32 v[94:95], 0
	v_mov_b64_e32 v[96:97], 0
	v_mov_b64_e32 v[98:99], 0
	v_mov_b64_e32 v[100:101], 0
	v_mov_b64_e32 v[102:103], 0
	v_mov_b64_e32 v[104:105], 0
	v_mov_b64_e32 v[106:107], 0
	v_mov_b64_e32 v[108:109], 0
	v_mov_b64_e32 v[110:111], 0
	v_mov_b64_e32 v[112:113], 0
	v_mov_b64_e32 v[114:115], 0
	v_mov_b64_e32 v[116:117], 0
	v_mov_b64_e32 v[118:119], 0
	v_mov_b64_e32 v[120:121], 0
	v_mov_b64_e32 v[122:123], 0
	v_mov_b64_e32 v[124:125], 0
	v_mov_b64_e32 v[126:127], 0
	v_readlane_b32 s84, v254, 54
	s_barrier
	s_branch .LBB0_1035
.LBB0_1033:
	v_mov_b32_e32 v0, 0
	s_mov_b32 s44, s80
	s_mov_b32 s33, s87
	s_mov_b32 s20, s74
	s_mov_b32 s64, s34
	s_mov_b64 s[62:63], s[54:55]
	s_mov_b64 s[60:61], s[48:49]
	s_mov_b32 s86, s81
	v_mov_b32_e32 v1, v0
	v_mov_b64_e32 v[2:3], 0
	v_mov_b64_e32 v[4:5], 0
	v_mov_b64_e32 v[6:7], 0
	v_mov_b64_e32 v[8:9], 0
	v_mov_b64_e32 v[10:11], 0
	v_mov_b64_e32 v[12:13], 0
	v_mov_b64_e32 v[14:15], 0
	v_mov_b64_e32 v[16:17], 0
	v_mov_b64_e32 v[18:19], 0
	v_mov_b64_e32 v[20:21], 0
	v_mov_b64_e32 v[22:23], 0
	v_mov_b64_e32 v[24:25], 0
	v_mov_b64_e32 v[26:27], 0
	v_mov_b64_e32 v[28:29], 0
	v_mov_b64_e32 v[30:31], 0
	v_mov_b64_e32 v[32:33], 0
	v_mov_b64_e32 v[34:35], 0
	v_mov_b64_e32 v[36:37], 0
	v_mov_b64_e32 v[38:39], 0
	v_mov_b64_e32 v[40:41], 0
	v_mov_b64_e32 v[42:43], 0
	v_mov_b64_e32 v[44:45], 0
	v_mov_b64_e32 v[46:47], 0
	v_mov_b64_e32 v[48:49], 0
	v_mov_b64_e32 v[50:51], 0
	v_mov_b64_e32 v[52:53], 0
	v_mov_b64_e32 v[54:55], 0
	v_mov_b64_e32 v[56:57], 0
	v_mov_b64_e32 v[58:59], 0
	v_mov_b64_e32 v[60:61], 0
	v_mov_b64_e32 v[62:63], 0
	v_mov_b64_e32 v[64:65], 0
	v_mov_b64_e32 v[66:67], 0
	v_mov_b64_e32 v[68:69], 0
	v_mov_b64_e32 v[70:71], 0
	v_mov_b64_e32 v[72:73], 0
	v_mov_b64_e32 v[74:75], 0
	v_mov_b64_e32 v[76:77], 0
	v_mov_b64_e32 v[78:79], 0
	v_mov_b64_e32 v[80:81], 0
	v_mov_b64_e32 v[82:83], 0
	v_mov_b64_e32 v[84:85], 0
	v_mov_b64_e32 v[86:87], 0
	v_mov_b64_e32 v[88:89], 0
	v_mov_b64_e32 v[90:91], 0
	v_mov_b64_e32 v[92:93], 0
	v_mov_b64_e32 v[94:95], 0
	v_mov_b64_e32 v[96:97], 0
	v_mov_b64_e32 v[98:99], 0
	v_mov_b64_e32 v[100:101], 0
	v_mov_b64_e32 v[102:103], 0
	v_mov_b64_e32 v[104:105], 0
	v_mov_b64_e32 v[106:107], 0
	v_mov_b64_e32 v[108:109], 0
	v_mov_b64_e32 v[110:111], 0
	v_mov_b64_e32 v[112:113], 0
	v_mov_b64_e32 v[114:115], 0
	v_mov_b64_e32 v[116:117], 0
	v_mov_b64_e32 v[118:119], 0
	v_mov_b64_e32 v[120:121], 0
	v_mov_b64_e32 v[122:123], 0
	v_mov_b64_e32 v[124:125], 0
	v_mov_b64_e32 v[126:127], 0

; template <class Epi, class Sched, bool ALIGN_EPI = false, bool SP2 = false>
; __device__ __forceinline__ void gemm_phase(PG8_LAS unsigned char* lds, const Gemm g, const Sched& S, const Epi& E) {
;     ...
;         const char* nA = has_next ? (const char*)g.A + (size_t)nxt.pm * tstepA + (size_t)nxt.z * g.azs + (size_t)(nxt.k0 >> 6) * kstA : cA; const char* nB = has_next ? (const char*)g.Bt + (size_t)nxt.pn * tstepB + (size_t)nxt.z * g.bzs + (size_t)nxt.k0 * 2 : cB;
;     ...
; #pragma unroll
;         for (int a = 0; a < 2; ++a)
; #pragma unroll
;             for (int b = 0; b < 2; ++b)
; #pragma unroll
;                 for (int m = 0; m < 4; ++m)
; #pragma unroll
;                     for (int n = 0; n < 2; ++n) acc[a][b][m][n] = (f32x4){0.f, 0.f, 0.f, 0.f};
;         cur = nxt; cA = nA; cB = nB; ++ui;
.LBB0_1306:
	s_ashr_i32 s41, s40, 31
	s_lshl_b64 s[4:5], s[40:41], 20
	v_readlane_b32 s12, v254, 41
	v_readlane_b32 s13, v254, 42
	s_add_u32 s44, s12, s4
	s_addc_u32 s45, s13, s5
	s_and_b64 s[4:5], s[42:43], exec
	s_cselect_b32 s4, s45, s51
	s_cselect_b32 s5, s44, s50
	s_ashr_i32 s39, s38, 31
	s_lshl_b64 s[12:13], s[38:39], 20
	s_add_u32 s48, s3, s12
	s_addc_u32 s49, s10, s13
	s_and_b64 s[12:13], s[42:43], exec
	s_cselect_b32 s12, s49, s53
	s_cselect_b32 s13, s48, s52
	s_add_u32 s50, s50, 0x80080
	s_addc_u32 s51, s51, 0
	s_add_u32 s39, s52, 0x100
	v_mov_b32_e32 v0, 0
	s_addc_u32 s41, s53, 0
	s_mov_b32 s63, -2
	v_mov_b32_e32 v1, v0
	v_mov_b64_e32 v[2:3], 0
	v_mov_b64_e32 v[4:5], 0
	v_mov_b64_e32 v[6:7], 0
	v_mov_b64_e32 v[16:17], 0
	v_mov_b64_e32 v[18:19], 0
	v_mov_b64_e32 v[20:21], 0
	v_mov_b64_e32 v[22:23], 0
	v_mov_b64_e32 v[32:33], 0
	v_mov_b64_e32 v[34:35], 0
	v_mov_b64_e32 v[36:37], 0
	v_mov_b64_e32 v[38:39], 0
	v_mov_b64_e32 v[48:49], 0
	v_mov_b64_e32 v[50:51], 0
	v_mov_b64_e32 v[52:53], 0
	v_mov_b64_e32 v[54:55], 0
	v_mov_b64_e32 v[8:9], 0
	v_mov_b64_e32 v[10:11], 0
	v_mov_b64_e32 v[12:13], 0
	v_mov_b64_e32 v[14:15], 0
	v_mov_b64_e32 v[24:25], 0
	v_mov_b64_e32 v[26:27], 0
	v_mov_b64_e32 v[28:29], 0
	v_mov_b64_e32 v[30:31], 0
	v_mov_b64_e32 v[40:41], 0
	v_mov_b64_e32 v[42:43], 0
	v_mov_b64_e32 v[44:45], 0
	v_mov_b64_e32 v[46:47], 0
	v_mov_b64_e32 v[56:57], 0
	v_mov_b64_e32 v[58:59], 0
	v_mov_b64_e32 v[60:61], 0
	v_mov_b64_e32 v[62:63], 0
	v_mov_b64_e32 v[64:65], 0
	v_mov_b64_e32 v[66:67], 0
	v_mov_b64_e32 v[68:69], 0
	v_mov_b64_e32 v[70:71], 0
	v_mov_b64_e32 v[80:81], 0
	v_mov_b64_e32 v[82:83], 0
	v_mov_b64_e32 v[84:85], 0
	v_mov_b64_e32 v[86:87], 0
	v_mov_b64_e32 v[96:97], 0
	v_mov_b64_e32 v[98:99], 0
	v_mov_b64_e32 v[100:101], 0
	v_mov_b64_e32 v[102:103], 0
	v_mov_b64_e32 v[112:113], 0
	v_mov_b64_e32 v[114:115], 0
	v_mov_b64_e32 v[116:117], 0
	v_mov_b64_e32 v[118:119], 0
	v_mov_b64_e32 v[72:73], 0
	v_mov_b64_e32 v[74:75], 0
	v_mov_b64_e32 v[76:77], 0
	v_mov_b64_e32 v[78:79], 0
	v_mov_b64_e32 v[88:89], 0
	v_mov_b64_e32 v[90:91], 0
	v_mov_b64_e32 v[92:93], 0
	v_mov_b64_e32 v[94:95], 0
	v_mov_b64_e32 v[104:105], 0
	v_mov_b64_e32 v[106:107], 0
	v_mov_b64_e32 v[108:109], 0
	v_mov_b64_e32 v[110:111], 0
	v_mov_b64_e32 v[120:121], 0
	v_mov_b64_e32 v[122:123], 0
	v_mov_b64_e32 v[124:125], 0
	v_mov_b64_e32 v[126:127], 0

;     __device__ __forceinline__ void operator()(const f32x4 (&acc)[2][2][4][2], const Unit& u, int wr, int wc, int fr, int fq) const {
;     ...
;         const int rloc0 = wr * 64 + fr, col0 = u.pn * BM + wc * 32 + 8 * fq;
;         if (u.z) {
;             float* sp = SLAB + ((size_t)(u.z - 1) * 512 + b * 256) * 2048;
; #pragma unroll
;             for (int ai = 0; ai < 2; ++ai)
; #pragma unroll
;                 for (int m = 0; m < 4; ++m) { float* dp = sp + (size_t)(rloc0 + ai * HALF + m * 16) * 2048 + col0;
; #pragma unroll
;                     for (int bj = 0; bj < 2; ++bj)
; #pragma unroll
;                         for (int n = 0; n < 2; ++n) *(f32x4*)(dp + bj * HALF + 4 * n) = acc[ai][bj][m][n]; }
; template <class Epi, class Sched, bool ALIGN_EPI = false, bool SP2 = false>
; __device__ __forceinline__ void gemm_phase(PG8_LAS unsigned char* lds, const Gemm g, const Sched& S, const Epi& E) {
;     ...
;     f32x4 acc[2][2][4][2];
; #pragma unroll
;     for (int a = 0; a < 2; ++a)
; #pragma unroll
;         for (int b = 0; b < 2; ++b)
; #pragma unroll
;             for (int m = 0; m < 4; ++m)
; #pragma unroll
;                 for (int n = 0; n < 2; ++n) acc[a][b][m][n] = (f32x4){0.f, 0.f, 0.f, 0.f};
;     bf16x8 At[4][2], B0[2][2], B1[2][2];
;     const char* cA = (const char*)g.A + (size_t)cur.pm * tstepA + (size_t)cur.z * g.azs + (size_t)(cur.k0 >> 6) * kstA; const char* cB = (const char*)g.Bt + (size_t)cur.pn * tstepB + (size_t)cur.z * g.bzs + (size_t)cur.k0 * 2;
;     S.a_ready(cur);
;     if constexpr (SP2) {
;         PG8_STAGE(PG8_SB(0, 0), cB, voffB); PG8_STAGE(PG8_SB(0, 1), cB + hstepB, voffB); PG8_STAGE(PG8_SA(0, 0), cA, voffA); PG8_STAGE(PG8_SA(0, 1), cA + hstepA, voffA);
;         if (wr == 1) PG8_BAR;
;         PG8_WAIT_V(2); PG8_BAR;
;         PG8_STAGE(PG8_SB(1, 0), cB + kstep, voffB); PG8_STAGE(PG8_SA(1, 0), cA + kstA, voffA); PG8_STAGE(PG8_SB(1, 1), cB + hstepB + kstep, voffB);
;         PG8_WAIT_V(6); PG8_BAR;
;     } else {
;         PG8_STAGE(PG8_SB(0, 0), cB, voffB); PG8_STAGE(PG8_SA(0, 0), cA, voffA); PG8_STAGE(PG8_SB(0, 1), cB + hstepB, voffB); PG8_STAGE(PG8_SA(0, 1), cA + hstepA, voffA);
;         if (wr == 1) PG8_BAR;
;         PG8_WAIT_V(4); PG8_BAR;
;         PG8_STAGE(PG8_SB(1, 0), cB + kstep, voffB); PG8_STAGE(PG8_SA(1, 0), cA + kstA, voffA); PG8_STAGE(PG8_SB(1, 1), cB + hstepB + kstep, voffB);
;         PG8_WAIT_V(6); PG8_BAR;
;     }
.LBB0_1382:
	v_lshrrev_b32_e32 v7, 1, v4
	v_and_b32_e32 v8, 24, v7
	v_and_b32_e32 v5, 15, v4
	v_lshlrev_b32_e32 v7, 1, v8
	v_lshlrev_b32_e32 v4, 2, v4
	v_lshl_or_b32 v6, s0, 6, v5
	v_lshl_or_b32 v5, v5, 6, v7
	s_lshl_b32 s0, s0, 13
	v_and_b32_e32 v4, 32, v4
	v_bitop3_b32 v9, v5, s0, v4 bitop3:0xde
	s_lshl_b32 s0, s1, 5
	s_and_b32 s5, s0, 0x60
	s_lshl_b32 s0, s5, 7
	s_add_u32 s3, s10, 0x110000
	s_mov_b64 s[64:65], 0x80
	s_addc_u32 s42, s11, 0
	s_add_i32 m0, s74, 0x18000
	v_lshl_add_u64 v[2:3], v[2:3], 0, s[64:65]
	s_waitcnt vmcnt(2)
	s_barrier
	global_load_lds_dwordx4 v[2:3], off
	s_add_i32 m0, s74, 0x1a000
	v_bitop3_b32 v177, v5, s0, v4 bitop3:0xde
	s_add_u32 s0, s34, 0x8000
	v_lshl_add_u64 v[0:1], v[0:1], 0, s[64:65]
	s_addc_u32 s1, s35, 0
	s_add_i32 s43, s74, 0x8000
	global_load_lds_dwordx4 v[0:1], off
	v_lshl_add_u64 v[0:1], s[0:1], 0, v[128:129]
	s_mov_b32 m0, s43
	s_add_i32 s56, s74, 0xa000
	global_load_lds_dwordx4 v[0:1], off
	v_lshl_add_u64 v[0:1], s[0:1], 0, v[132:133]
	s_add_u32 s0, s40, 0x160080
	s_mov_b32 m0, s56
	s_addc_u32 s1, s41, 0
	global_load_lds_dwordx4 v[0:1], off
	s_add_i32 m0, s74, 0x1c000
	v_lshl_add_u64 v[0:1], s[0:1], 0, v[130:131]
	global_load_lds_dwordx4 v[0:1], off
	v_lshl_add_u64 v[0:1], s[0:1], 0, v[134:135]
	s_add_i32 m0, s74, 0x1e000
	v_ashrrev_i32_e32 v7, 31, v6
	global_load_lds_dwordx4 v[0:1], off
	v_or_b32_e32 v0, 16, v6
	v_lshlrev_b64 v[136:137], 13, v[6:7]
	v_ashrrev_i32_e32 v1, 31, v0
	s_mov_b64 s[0:1], 0x100000
	v_lshlrev_b64 v[138:139], 13, v[0:1]
	v_or_b32_e32 v0, 32, v6
	v_lshl_add_u64 v[144:145], v[136:137], 0, s[0:1]
	s_mov_b64 s[0:1], 0x120000
	v_ashrrev_i32_e32 v1, 31, v0
	v_lshl_add_u64 v[146:147], v[136:137], 0, s[0:1]
	s_mov_b64 s[0:1], 0x140000
	v_lshlrev_b64 v[140:141], 13, v[0:1]
	v_or_b32_e32 v0, 48, v6
	v_lshl_add_u64 v[148:149], v[136:137], 0, s[0:1]
	s_mov_b64 s[0:1], 0x160000
	s_waitcnt vmcnt(6)
	v_ashrrev_i32_e32 v1, 31, v0
	v_lshl_add_u64 v[150:151], v[136:137], 0, s[0:1]
	v_readlane_b32 s0, v255, 12
	s_cmpk_lt_u32 s4, 0x100
	v_lshlrev_b64 v[142:143], 13, v[0:1]
	v_lshlrev_b64 v[0:1], 12, v[6:7]
	v_readlane_b32 s1, v255, 13
	s_cselect_b64 s[66:67], -1, 0
	v_or_b32_e32 v178, s5, v8
	v_lshl_add_u64 v[152:153], s[0:1], 0, v[0:1]
	s_movk_i32 s57, 0x58
	v_mov_b64_e32 v[154:155], 0x1ff
	s_add_i32 s10, 0, 0x10000
	s_add_i32 s11, 0, 0x14000
	v_add_u32_e32 v179, 0, v9
	v_mov_b64_e32 v[156:157], 0x1e8481
	s_mov_b32 s33, 0
	s_mov_b32 s86, 0
	v_mov_b64_e32 v[0:1], 0
	v_mov_b64_e32 v[2:3], 0
	v_mov_b64_e32 v[4:5], 0
	v_mov_b64_e32 v[6:7], 0
	v_mov_b64_e32 v[8:9], 0
	v_mov_b64_e32 v[10:11], 0
	v_mov_b64_e32 v[12:13], 0
	v_mov_b64_e32 v[14:15], 0
	v_mov_b64_e32 v[16:17], 0
	v_mov_b64_e32 v[18:19], 0
	v_mov_b64_e32 v[20:21], 0
	v_mov_b64_e32 v[22:23], 0
	v_mov_b64_e32 v[24:25], 0
	v_mov_b64_e32 v[26:27], 0
	v_mov_b64_e32 v[28:29], 0
	v_mov_b64_e32 v[30:31], 0
	v_mov_b64_e32 v[32:33], 0
	v_mov_b64_e32 v[34:35], 0
	v_mov_b64_e32 v[36:37], 0
	v_mov_b64_e32 v[38:39], 0
	v_mov_b64_e32 v[40:41], 0
	v_mov_b64_e32 v[42:43], 0
	v_mov_b64_e32 v[44:45], 0
	v_mov_b64_e32 v[46:47], 0
	v_mov_b64_e32 v[48:49], 0
	v_mov_b64_e32 v[50:51], 0
	v_mov_b64_e32 v[52:53], 0
	v_mov_b64_e32 v[54:55], 0
	v_mov_b64_e32 v[56:57], 0
	v_mov_b64_e32 v[58:59], 0
	v_mov_b64_e32 v[60:61], 0
	v_mov_b64_e32 v[62:63], 0
	v_mov_b64_e32 v[64:65], 0
	v_mov_b64_e32 v[66:67], 0
	v_mov_b64_e32 v[68:69], 0
	v_mov_b64_e32 v[70:71], 0
	v_mov_b64_e32 v[72:73], 0
	v_mov_b64_e32 v[74:75], 0
	v_mov_b64_e32 v[76:77], 0
	v_mov_b64_e32 v[78:79], 0
	v_mov_b64_e32 v[80:81], 0
	v_mov_b64_e32 v[82:83], 0
	v_mov_b64_e32 v[84:85], 0
	v_mov_b64_e32 v[86:87], 0
	v_mov_b64_e32 v[88:89], 0
	v_mov_b64_e32 v[90:91], 0
	v_mov_b64_e32 v[92:93], 0
	v_mov_b64_e32 v[94:95], 0
	v_mov_b64_e32 v[96:97], 0
	v_mov_b64_e32 v[98:99], 0
	v_mov_b64_e32 v[100:101], 0
	v_mov_b64_e32 v[102:103], 0
	v_mov_b64_e32 v[104:105], 0
	v_mov_b64_e32 v[106:107], 0
	v_mov_b64_e32 v[108:109], 0
	v_mov_b64_e32 v[110:111], 0
	v_mov_b64_e32 v[112:113], 0
	v_mov_b64_e32 v[114:115], 0
	v_mov_b64_e32 v[116:117], 0
	v_mov_b64_e32 v[118:119], 0
	v_mov_b64_e32 v[120:121], 0
	v_mov_b64_e32 v[122:123], 0
	v_mov_b64_e32 v[124:125], 0
	v_mov_b64_e32 v[126:127], 0
	s_barrier
	s_branch .LBB0_1385
.LBB0_1383:
	v_mov_b32_e32 v0, 0
	s_mov_b32 s57, s81
	s_mov_b32 s33, s87
	s_mov_b32 s84, s76
	s_mov_b32 s20, s80
	s_mov_b64 s[40:41], s[62:63]
	s_mov_b64 s[34:35], s[60:61]
	s_mov_b32 s86, s82
	v_mov_b32_e32 v1, v0
	v_mov_b64_e32 v[2:3], 0
	v_mov_b64_e32 v[4:5], 0
	v_mov_b64_e32 v[6:7], 0
	v_mov_b64_e32 v[8:9], 0
	v_mov_b64_e32 v[10:11], 0
	v_mov_b64_e32 v[12:13], 0
	v_mov_b64_e32 v[14:15], 0
	v_mov_b64_e32 v[16:17], 0
	v_mov_b64_e32 v[18:19], 0
	v_mov_b64_e32 v[20:21], 0
	v_mov_b64_e32 v[22:23], 0
	v_mov_b64_e32 v[24:25], 0
	v_mov_b64_e32 v[26:27], 0
	v_mov_b64_e32 v[28:29], 0
	v_mov_b64_e32 v[30:31], 0
	v_mov_b64_e32 v[32:33], 0
	v_mov_b64_e32 v[34:35], 0
	v_mov_b64_e32 v[36:37], 0
	v_mov_b64_e32 v[38:39], 0
	v_mov_b64_e32 v[40:41], 0
	v_mov_b64_e32 v[42:43], 0
	v_mov_b64_e32 v[44:45], 0
	v_mov_b64_e32 v[46:47], 0
	v_mov_b64_e32 v[48:49], 0
	v_mov_b64_e32 v[50:51], 0
	v_mov_b64_e32 v[52:53], 0
	v_mov_b64_e32 v[54:55], 0
	v_mov_b64_e32 v[56:57], 0
	v_mov_b64_e32 v[58:59], 0
	v_mov_b64_e32 v[60:61], 0
	v_mov_b64_e32 v[62:63], 0
	v_mov_b64_e32 v[64:65], 0
	v_mov_b64_e32 v[66:67], 0
	v_mov_b64_e32 v[68:69], 0
	v_mov_b64_e32 v[70:71], 0
	v_mov_b64_e32 v[72:73], 0
	v_mov_b64_e32 v[74:75], 0
	v_mov_b64_e32 v[76:77], 0
	v_mov_b64_e32 v[78:79], 0
	v_mov_b64_e32 v[80:81], 0
	v_mov_b64_e32 v[82:83], 0
	v_mov_b64_e32 v[84:85], 0
	v_mov_b64_e32 v[86:87], 0
	v_mov_b64_e32 v[88:89], 0
	v_mov_b64_e32 v[90:91], 0
	v_mov_b64_e32 v[92:93], 0
	v_mov_b64_e32 v[94:95], 0
	v_mov_b64_e32 v[96:97], 0
	v_mov_b64_e32 v[98:99], 0
	v_mov_b64_e32 v[100:101], 0
	v_mov_b64_e32 v[102:103], 0
	v_mov_b64_e32 v[104:105], 0
	v_mov_b64_e32 v[106:107], 0
	v_mov_b64_e32 v[108:109], 0
	v_mov_b64_e32 v[110:111], 0
	v_mov_b64_e32 v[112:113], 0
	v_mov_b64_e32 v[114:115], 0
	v_mov_b64_e32 v[116:117], 0
	v_mov_b64_e32 v[118:119], 0
	v_mov_b64_e32 v[120:121], 0
	v_mov_b64_e32 v[122:123], 0
	v_mov_b64_e32 v[124:125], 0
	v_mov_b64_e32 v[126:127], 0

; template <class Epi, class Sched, bool ALIGN_EPI = false, bool SP2 = false>
; __device__ __forceinline__ void gemm_phase(PG8_LAS unsigned char* lds, const Gemm g, const Sched& S, const Epi& E) {
;     ...
;         const char* nA = has_next ? (const char*)g.A + (size_t)nxt.pm * tstepA + (size_t)nxt.z * g.azs + (size_t)(nxt.k0 >> 6) * kstA : cA; const char* nB = has_next ? (const char*)g.Bt + (size_t)nxt.pn * tstepB + (size_t)nxt.z * g.bzs + (size_t)nxt.k0 * 2 : cB;
;     ...
; #pragma unroll
;         for (int a = 0; a < 2; ++a)
; #pragma unroll
;             for (int b = 0; b < 2; ++b)
; #pragma unroll
;                 for (int m = 0; m < 4; ++m)
; #pragma unroll
;                     for (int n = 0; n < 2; ++n) acc[a][b][m][n] = (f32x4){0.f, 0.f, 0.f, 0.f};
;         cur = nxt; cA = nA; cB = nB; ++ui;
.LBB0_1656:
	s_ashr_i32 s41, s40, 31
	s_lshl_b64 s[4:5], s[40:41], 20
	v_readlane_b32 s12, v254, 41
	v_readlane_b32 s13, v254, 42
	s_add_u32 s48, s12, s4
	s_addc_u32 s49, s13, s5
	s_and_b64 s[4:5], s[44:45], exec
	s_cselect_b32 s4, s49, s51
	s_cselect_b32 s5, s48, s50
	s_ashr_i32 s39, s38, 31
	s_lshl_b64 s[12:13], s[38:39], 20
	s_add_u32 s54, s3, s12
	s_addc_u32 s55, s10, s13
	s_and_b64 s[12:13], s[44:45], exec
	s_cselect_b32 s12, s55, s53
	s_cselect_b32 s13, s54, s52
	s_add_u32 s50, s50, 0x80080
	s_addc_u32 s51, s51, 0
	s_add_u32 s39, s52, 0x100
	v_mov_b32_e32 v0, 0
	s_addc_u32 s41, s53, 0
	s_mov_b32 s63, -2
	v_mov_b32_e32 v1, v0
	v_mov_b64_e32 v[2:3], 0
	v_mov_b64_e32 v[4:5], 0
	v_mov_b64_e32 v[6:7], 0
	v_mov_b64_e32 v[16:17], 0
	v_mov_b64_e32 v[18:19], 0
	v_mov_b64_e32 v[20:21], 0
	v_mov_b64_e32 v[22:23], 0
	v_mov_b64_e32 v[32:33], 0
	v_mov_b64_e32 v[34:35], 0
	v_mov_b64_e32 v[36:37], 0
	v_mov_b64_e32 v[38:39], 0
	v_mov_b64_e32 v[48:49], 0
	v_mov_b64_e32 v[50:51], 0
	v_mov_b64_e32 v[52:53], 0
	v_mov_b64_e32 v[54:55], 0
	v_mov_b64_e32 v[8:9], 0
	v_mov_b64_e32 v[10:11], 0
	v_mov_b64_e32 v[12:13], 0
	v_mov_b64_e32 v[14:15], 0
	v_mov_b64_e32 v[24:25], 0
	v_mov_b64_e32 v[26:27], 0
	v_mov_b64_e32 v[28:29], 0
	v_mov_b64_e32 v[30:31], 0
	v_mov_b64_e32 v[40:41], 0
	v_mov_b64_e32 v[42:43], 0
	v_mov_b64_e32 v[44:45], 0
	v_mov_b64_e32 v[46:47], 0
	v_mov_b64_e32 v[56:57], 0
	v_mov_b64_e32 v[58:59], 0
	v_mov_b64_e32 v[60:61], 0
	v_mov_b64_e32 v[62:63], 0
	v_mov_b64_e32 v[64:65], 0
	v_mov_b64_e32 v[66:67], 0
	v_mov_b64_e32 v[68:69], 0
	v_mov_b64_e32 v[70:71], 0
	v_mov_b64_e32 v[80:81], 0
	v_mov_b64_e32 v[82:83], 0
	v_mov_b64_e32 v[84:85], 0
	v_mov_b64_e32 v[86:87], 0
	v_mov_b64_e32 v[96:97], 0
	v_mov_b64_e32 v[98:99], 0
	v_mov_b64_e32 v[100:101], 0
	v_mov_b64_e32 v[102:103], 0
	v_mov_b64_e32 v[112:113], 0
	v_mov_b64_e32 v[114:115], 0
	v_mov_b64_e32 v[116:117], 0
	v_mov_b64_e32 v[118:119], 0
	v_mov_b64_e32 v[72:73], 0
	v_mov_b64_e32 v[74:75], 0
	v_mov_b64_e32 v[76:77], 0
	v_mov_b64_e32 v[78:79], 0
	v_mov_b64_e32 v[88:89], 0
	v_mov_b64_e32 v[90:91], 0
	v_mov_b64_e32 v[92:93], 0
	v_mov_b64_e32 v[94:95], 0
	v_mov_b64_e32 v[104:105], 0
	v_mov_b64_e32 v[106:107], 0
	v_mov_b64_e32 v[108:109], 0
	v_mov_b64_e32 v[110:111], 0
	v_mov_b64_e32 v[120:121], 0
	v_mov_b64_e32 v[122:123], 0
	v_mov_b64_e32 v[124:125], 0
	v_mov_b64_e32 v[126:127], 0

;     __device__ __forceinline__ void operator()(const f32x4 (&acc)[2][2][4][2], const Unit& u, int wr, int wc, int fr, int fq) const {
;     ...
;         const int rloc0 = wr * 64 + fr, col0 = u.pn * BM + wc * 32 + 8 * fq;
;         if (u.z) {
;             float* sp = SLAB + ((size_t)(u.z - 1) * 512 + b * 256) * 2048;
; #pragma unroll
;             for (int ai = 0; ai < 2; ++ai)
; #pragma unroll
;                 for (int m = 0; m < 4; ++m) { float* dp = sp + (size_t)(rloc0 + ai * HALF + m * 16) * 2048 + col0;
; #pragma unroll
;                     for (int bj = 0; bj < 2; ++bj)
; #pragma unroll
;                         for (int n = 0; n < 2; ++n) *(f32x4*)(dp + bj * HALF + 4 * n) = acc[ai][bj][m][n]; }
; template <class Epi, class Sched, bool ALIGN_EPI = false, bool SP2 = false>
; __device__ __forceinline__ void gemm_phase(PG8_LAS unsigned char* lds, const Gemm g, const Sched& S, const Epi& E) {
;     ...
;     f32x4 acc[2][2][4][2];
; #pragma unroll
;     for (int a = 0; a < 2; ++a)
; #pragma unroll
;         for (int b = 0; b < 2; ++b)
; #pragma unroll
;             for (int m = 0; m < 4; ++m)
; #pragma unroll
;                 for (int n = 0; n < 2; ++n) acc[a][b][m][n] = (f32x4){0.f, 0.f, 0.f, 0.f};
;     bf16x8 At[4][2], B0[2][2], B1[2][2];
;     const char* cA = (const char*)g.A + (size_t)cur.pm * tstepA + (size_t)cur.z * g.azs + (size_t)(cur.k0 >> 6) * kstA; const char* cB = (const char*)g.Bt + (size_t)cur.pn * tstepB + (size_t)cur.z * g.bzs + (size_t)cur.k0 * 2;
;     S.a_ready(cur);
;     if constexpr (SP2) {
;         PG8_STAGE(PG8_SB(0, 0), cB, voffB); PG8_STAGE(PG8_SB(0, 1), cB + hstepB, voffB); PG8_STAGE(PG8_SA(0, 0), cA, voffA); PG8_STAGE(PG8_SA(0, 1), cA + hstepA, voffA);
;         if (wr == 1) PG8_BAR;
;         PG8_WAIT_V(2); PG8_BAR;
;         PG8_STAGE(PG8_SB(1, 0), cB + kstep, voffB); PG8_STAGE(PG8_SA(1, 0), cA + kstA, voffA); PG8_STAGE(PG8_SB(1, 1), cB + hstepB + kstep, voffB);
;         PG8_WAIT_V(6); PG8_BAR;
;     } else {
;         PG8_STAGE(PG8_SB(0, 0), cB, voffB); PG8_STAGE(PG8_SA(0, 0), cA, voffA); PG8_STAGE(PG8_SB(0, 1), cB + hstepB, voffB); PG8_STAGE(PG8_SA(0, 1), cA + hstepA, voffA);
;         if (wr == 1) PG8_BAR;
;         PG8_WAIT_V(4); PG8_BAR;
;         PG8_STAGE(PG8_SB(1, 0), cB + kstep, voffB); PG8_STAGE(PG8_SA(1, 0), cA + kstA, voffA); PG8_STAGE(PG8_SB(1, 1), cB + hstepB + kstep, voffB);
;         PG8_WAIT_V(6); PG8_BAR;
;     }
.LBB0_1732:
	v_lshrrev_b32_e32 v7, 1, v4
	v_and_b32_e32 v8, 24, v7
	v_and_b32_e32 v5, 15, v4
	v_lshlrev_b32_e32 v7, 1, v8
	v_lshlrev_b32_e32 v4, 2, v4
	v_lshl_or_b32 v6, s0, 6, v5
	v_lshl_or_b32 v5, v5, 6, v7
	s_lshl_b32 s0, s0, 13
	v_and_b32_e32 v4, 32, v4
	v_bitop3_b32 v9, v5, s0, v4 bitop3:0xde
	s_lshl_b32 s0, s1, 5
	s_and_b32 s5, s0, 0x60
	s_lshl_b32 s0, s5, 7
	s_add_u32 s3, s10, 0x13a000
	s_mov_b64 s[54:55], 0x80
	s_addc_u32 s94, s11, 0
	s_add_i32 m0, s74, 0x18000
	v_lshl_add_u64 v[2:3], v[2:3], 0, s[54:55]
	s_waitcnt vmcnt(2)
	s_barrier
	global_load_lds_dwordx4 v[2:3], off
	s_add_i32 m0, s74, 0x1a000
	v_bitop3_b32 v177, v5, s0, v4 bitop3:0xde
	s_add_u32 s0, s34, 0x8000
	v_lshl_add_u64 v[0:1], v[0:1], 0, s[54:55]
	s_addc_u32 s1, s35, 0
	s_add_i32 s95, s74, 0x8000
	global_load_lds_dwordx4 v[0:1], off
	v_lshl_add_u64 v[0:1], s[0:1], 0, v[128:129]
	s_mov_b32 m0, s95
	s_add_i32 s96, s74, 0xa000
	global_load_lds_dwordx4 v[0:1], off
	v_lshl_add_u64 v[0:1], s[0:1], 0, v[132:133]
	s_add_u32 s0, s40, 0x160080
	s_mov_b32 m0, s96
	s_addc_u32 s1, s41, 0
	global_load_lds_dwordx4 v[0:1], off
	s_add_i32 m0, s74, 0x1c000
	v_lshl_add_u64 v[0:1], s[0:1], 0, v[130:131]
	global_load_lds_dwordx4 v[0:1], off
	v_lshl_add_u64 v[0:1], s[0:1], 0, v[134:135]
	s_add_i32 m0, s74, 0x1e000
	v_ashrrev_i32_e32 v7, 31, v6
	global_load_lds_dwordx4 v[0:1], off
	v_or_b32_e32 v0, 16, v6
	v_lshlrev_b64 v[136:137], 13, v[6:7]
	v_ashrrev_i32_e32 v1, 31, v0
	s_mov_b64 s[0:1], 0x100000
	v_lshlrev_b64 v[138:139], 13, v[0:1]
	v_or_b32_e32 v0, 32, v6
	v_lshl_add_u64 v[144:145], v[136:137], 0, s[0:1]
	s_mov_b64 s[0:1], 0x120000
	v_ashrrev_i32_e32 v1, 31, v0
	v_lshl_add_u64 v[146:147], v[136:137], 0, s[0:1]
	s_mov_b64 s[0:1], 0x140000
	v_lshlrev_b64 v[140:141], 13, v[0:1]
	v_or_b32_e32 v0, 48, v6
	v_lshl_add_u64 v[148:149], v[136:137], 0, s[0:1]
	s_mov_b64 s[0:1], 0x160000
	s_waitcnt vmcnt(6)
	v_ashrrev_i32_e32 v1, 31, v0
	v_lshl_add_u64 v[150:151], v[136:137], 0, s[0:1]
	v_readlane_b32 s0, v255, 12
	s_cmpk_lt_u32 s4, 0x100
	v_lshlrev_b64 v[142:143], 13, v[0:1]
	v_lshlrev_b64 v[0:1], 12, v[6:7]
	v_readlane_b32 s1, v255, 13
	s_cselect_b64 s[56:57], -1, 0
	v_or_b32_e32 v178, s5, v8
	v_lshl_add_u64 v[152:153], s[0:1], 0, v[0:1]
	s_movk_i32 s97, 0x58
	v_mov_b64_e32 v[154:155], 0x1ff
	s_add_i32 s10, 0, 0x10000
	s_add_i32 s11, 0, 0x14000
	v_add_u32_e32 v179, 0, v9
	v_mov_b64_e32 v[156:157], 0x1e8481
	s_mov_b32 s33, 0
	s_mov_b32 s86, 0
	v_mov_b64_e32 v[0:1], 0
	v_mov_b64_e32 v[2:3], 0
	v_mov_b64_e32 v[4:5], 0
	v_mov_b64_e32 v[6:7], 0
	v_mov_b64_e32 v[8:9], 0
	v_mov_b64_e32 v[10:11], 0
	v_mov_b64_e32 v[12:13], 0
	v_mov_b64_e32 v[14:15], 0
	v_mov_b64_e32 v[16:17], 0
	v_mov_b64_e32 v[18:19], 0
	v_mov_b64_e32 v[20:21], 0
	v_mov_b64_e32 v[22:23], 0
	v_mov_b64_e32 v[24:25], 0
	v_mov_b64_e32 v[26:27], 0
	v_mov_b64_e32 v[28:29], 0
	v_mov_b64_e32 v[30:31], 0
	v_mov_b64_e32 v[32:33], 0
	v_mov_b64_e32 v[34:35], 0
	v_mov_b64_e32 v[36:37], 0
	v_mov_b64_e32 v[38:39], 0
	v_mov_b64_e32 v[40:41], 0
	v_mov_b64_e32 v[42:43], 0
	v_mov_b64_e32 v[44:45], 0
	v_mov_b64_e32 v[46:47], 0
	v_mov_b64_e32 v[48:49], 0
	v_mov_b64_e32 v[50:51], 0
	v_mov_b64_e32 v[52:53], 0
	v_mov_b64_e32 v[54:55], 0
	v_mov_b64_e32 v[56:57], 0
	v_mov_b64_e32 v[58:59], 0
	v_mov_b64_e32 v[60:61], 0
	v_mov_b64_e32 v[62:63], 0
	v_mov_b64_e32 v[64:65], 0
	v_mov_b64_e32 v[66:67], 0
	v_mov_b64_e32 v[68:69], 0
	v_mov_b64_e32 v[70:71], 0
	v_mov_b64_e32 v[72:73], 0
	v_mov_b64_e32 v[74:75], 0
	v_mov_b64_e32 v[76:77], 0
	v_mov_b64_e32 v[78:79], 0
	v_mov_b64_e32 v[80:81], 0
	v_mov_b64_e32 v[82:83], 0
	v_mov_b64_e32 v[84:85], 0
	v_mov_b64_e32 v[86:87], 0
	v_mov_b64_e32 v[88:89], 0
	v_mov_b64_e32 v[90:91], 0
	v_mov_b64_e32 v[92:93], 0
	v_mov_b64_e32 v[94:95], 0
	v_mov_b64_e32 v[96:97], 0
	v_mov_b64_e32 v[98:99], 0
	v_mov_b64_e32 v[100:101], 0
	v_mov_b64_e32 v[102:103], 0
	v_mov_b64_e32 v[104:105], 0
	v_mov_b64_e32 v[106:107], 0
	v_mov_b64_e32 v[108:109], 0
	v_mov_b64_e32 v[110:111], 0
	v_mov_b64_e32 v[112:113], 0
	v_mov_b64_e32 v[114:115], 0
	v_mov_b64_e32 v[116:117], 0
	v_mov_b64_e32 v[118:119], 0
	v_mov_b64_e32 v[120:121], 0
	v_mov_b64_e32 v[122:123], 0
	v_mov_b64_e32 v[124:125], 0
	v_mov_b64_e32 v[126:127], 0
	s_barrier
	s_branch .LBB0_1735
.LBB0_1733:
	v_mov_b32_e32 v0, 0
	s_mov_b32 s97, s81
	s_mov_b32 s33, s87
	s_mov_b32 s70, s84
	s_mov_b32 s20, s80
	s_mov_b64 s[40:41], s[60:61]
	s_mov_b64 s[34:35], s[58:59]
	s_mov_b32 s86, s82
	v_mov_b32_e32 v1, v0
	v_mov_b64_e32 v[2:3], 0
	v_mov_b64_e32 v[4:5], 0
	v_mov_b64_e32 v[6:7], 0
	v_mov_b64_e32 v[8:9], 0
	v_mov_b64_e32 v[10:11], 0
	v_mov_b64_e32 v[12:13], 0
	v_mov_b64_e32 v[14:15], 0
	v_mov_b64_e32 v[16:17], 0
	v_mov_b64_e32 v[18:19], 0
	v_mov_b64_e32 v[20:21], 0
	v_mov_b64_e32 v[22:23], 0
	v_mov_b64_e32 v[24:25], 0
	v_mov_b64_e32 v[26:27], 0
	v_mov_b64_e32 v[28:29], 0
	v_mov_b64_e32 v[30:31], 0
	v_mov_b64_e32 v[32:33], 0
	v_mov_b64_e32 v[34:35], 0
	v_mov_b64_e32 v[36:37], 0
	v_mov_b64_e32 v[38:39], 0
	v_mov_b64_e32 v[40:41], 0
	v_mov_b64_e32 v[42:43], 0
	v_mov_b64_e32 v[44:45], 0
	v_mov_b64_e32 v[46:47], 0
	v_mov_b64_e32 v[48:49], 0
	v_mov_b64_e32 v[50:51], 0
	v_mov_b64_e32 v[52:53], 0
	v_mov_b64_e32 v[54:55], 0
	v_mov_b64_e32 v[56:57], 0
	v_mov_b64_e32 v[58:59], 0
	v_mov_b64_e32 v[60:61], 0
	v_mov_b64_e32 v[62:63], 0
	v_mov_b64_e32 v[64:65], 0
	v_mov_b64_e32 v[66:67], 0
	v_mov_b64_e32 v[68:69], 0
	v_mov_b64_e32 v[70:71], 0
	v_mov_b64_e32 v[72:73], 0
	v_mov_b64_e32 v[74:75], 0
	v_mov_b64_e32 v[76:77], 0
	v_mov_b64_e32 v[78:79], 0
	v_mov_b64_e32 v[80:81], 0
	v_mov_b64_e32 v[82:83], 0
	v_mov_b64_e32 v[84:85], 0
	v_mov_b64_e32 v[86:87], 0
	v_mov_b64_e32 v[88:89], 0
	v_mov_b64_e32 v[90:91], 0
	v_mov_b64_e32 v[92:93], 0
	v_mov_b64_e32 v[94:95], 0
	v_mov_b64_e32 v[96:97], 0
	v_mov_b64_e32 v[98:99], 0
	v_mov_b64_e32 v[100:101], 0
	v_mov_b64_e32 v[102:103], 0
	v_mov_b64_e32 v[104:105], 0
	v_mov_b64_e32 v[106:107], 0
	v_mov_b64_e32 v[108:109], 0
	v_mov_b64_e32 v[110:111], 0
	v_mov_b64_e32 v[112:113], 0
	v_mov_b64_e32 v[114:115], 0
	v_mov_b64_e32 v[116:117], 0
	v_mov_b64_e32 v[118:119], 0
	v_mov_b64_e32 v[120:121], 0
	v_mov_b64_e32 v[122:123], 0
	v_mov_b64_e32 v[124:125], 0
	v_mov_b64_e32 v[126:127], 0

; template <class Epi, class Sched, bool ALIGN_EPI = false, bool SP2 = false>
; __device__ __forceinline__ void gemm_phase(PG8_LAS unsigned char* lds, const Gemm g, const Sched& S, const Epi& E) {
;     ...
;         const char* nA = has_next ? (const char*)g.A + (size_t)nxt.pm * tstepA + (size_t)nxt.z * g.azs + (size_t)(nxt.k0 >> 6) * kstA : cA; const char* nB = has_next ? (const char*)g.Bt + (size_t)nxt.pn * tstepB + (size_t)nxt.z * g.bzs + (size_t)nxt.k0 * 2 : cB;
;     ...
; #pragma unroll
;         for (int a = 0; a < 2; ++a)
; #pragma unroll
;             for (int b = 0; b < 2; ++b)
; #pragma unroll
;                 for (int m = 0; m < 4; ++m)
; #pragma unroll
;                     for (int n = 0; n < 2; ++n) acc[a][b][m][n] = (f32x4){0.f, 0.f, 0.f, 0.f};
;         cur = nxt; cA = nA; cB = nB; ++ui;
.LBB0_2049:
	s_ashr_i32 s61, s60, 31
	s_lshl_b64 s[4:5], s[60:61], 20
	v_readlane_b32 s10, v254, 41
	v_readlane_b32 s11, v254, 42
	s_add_u32 s62, s10, s4
	s_addc_u32 s63, s11, s5
	s_and_b64 s[4:5], s[42:43], exec
	s_cselect_b32 s1, s63, s21
	s_cselect_b32 s3, s62, s20
	s_ashr_i32 s59, s58, 31
	s_lshl_b64 s[4:5], s[58:59], 20
	s_add_u32 s64, s72, s4
	s_addc_u32 s65, s73, s5
	s_and_b64 s[4:5], s[42:43], exec
	s_cselect_b32 s4, s65, s39
	s_cselect_b32 s5, s64, s38
	s_add_u32 s20, s20, 0x80080
	s_addc_u32 s21, s21, 0
	s_add_u32 s10, s38, 0x100
	v_mov_b32_e32 v0, 0
	s_addc_u32 s11, s39, 0
	s_mov_b32 s12, -2
	v_mov_b32_e32 v1, v0
	v_mov_b64_e32 v[2:3], 0
	v_mov_b64_e32 v[4:5], 0
	v_mov_b64_e32 v[6:7], 0
	v_mov_b64_e32 v[16:17], 0
	v_mov_b64_e32 v[18:19], 0
	v_mov_b64_e32 v[20:21], 0
	v_mov_b64_e32 v[22:23], 0
	v_mov_b64_e32 v[32:33], 0
	v_mov_b64_e32 v[34:35], 0
	v_mov_b64_e32 v[36:37], 0
	v_mov_b64_e32 v[38:39], 0
	v_mov_b64_e32 v[48:49], 0
	v_mov_b64_e32 v[50:51], 0
	v_mov_b64_e32 v[52:53], 0
	v_mov_b64_e32 v[54:55], 0
	v_mov_b64_e32 v[8:9], 0
	v_mov_b64_e32 v[10:11], 0
	v_mov_b64_e32 v[12:13], 0
	v_mov_b64_e32 v[14:15], 0
	v_mov_b64_e32 v[24:25], 0
	v_mov_b64_e32 v[26:27], 0
	v_mov_b64_e32 v[28:29], 0
	v_mov_b64_e32 v[30:31], 0
	v_mov_b64_e32 v[40:41], 0
	v_mov_b64_e32 v[42:43], 0
	v_mov_b64_e32 v[44:45], 0
	v_mov_b64_e32 v[46:47], 0
	v_mov_b64_e32 v[56:57], 0
	v_mov_b64_e32 v[58:59], 0
	v_mov_b64_e32 v[60:61], 0
	v_mov_b64_e32 v[62:63], 0
	v_mov_b64_e32 v[64:65], 0
	v_mov_b64_e32 v[66:67], 0
	v_mov_b64_e32 v[68:69], 0
	v_mov_b64_e32 v[70:71], 0
	v_mov_b64_e32 v[80:81], 0
	v_mov_b64_e32 v[82:83], 0
	v_mov_b64_e32 v[84:85], 0
	v_mov_b64_e32 v[86:87], 0
	v_mov_b64_e32 v[96:97], 0
	v_mov_b64_e32 v[98:99], 0
	v_mov_b64_e32 v[100:101], 0
	v_mov_b64_e32 v[102:103], 0
	v_mov_b64_e32 v[112:113], 0
	v_mov_b64_e32 v[114:115], 0
	v_mov_b64_e32 v[116:117], 0
	v_mov_b64_e32 v[118:119], 0
	v_mov_b64_e32 v[72:73], 0
	v_mov_b64_e32 v[74:75], 0
	v_mov_b64_e32 v[76:77], 0
	v_mov_b64_e32 v[78:79], 0
	v_mov_b64_e32 v[88:89], 0
	v_mov_b64_e32 v[90:91], 0
	v_mov_b64_e32 v[92:93], 0
	v_mov_b64_e32 v[94:95], 0
	v_mov_b64_e32 v[104:105], 0
	v_mov_b64_e32 v[106:107], 0
	v_mov_b64_e32 v[108:109], 0
	v_mov_b64_e32 v[110:111], 0
	v_mov_b64_e32 v[120:121], 0
	v_mov_b64_e32 v[122:123], 0
	v_mov_b64_e32 v[124:125], 0
	v_mov_b64_e32 v[126:127], 0

;     __device__ __forceinline__ void operator()(const f32x4 (&acc)[2][2][4][2], const Unit& u, int wr, int wc, int fr, int fq) const {
;     ...
;         const int rloc0 = wr * 64 + fr, col0 = u.pn * BM + wc * 32 + 8 * fq;
;         if (u.z) {
;             float* sp = SLAB + ((size_t)(u.z - 1) * 512 + b * 256) * 2048;
; #pragma unroll
;             for (int ai = 0; ai < 2; ++ai)
; #pragma unroll
;                 for (int m = 0; m < 4; ++m) { float* dp = sp + (size_t)(rloc0 + ai * HALF + m * 16) * 2048 + col0;
; #pragma unroll
;                     for (int bj = 0; bj < 2; ++bj)
; #pragma unroll
;                         for (int n = 0; n < 2; ++n) *(f32x4*)(dp + bj * HALF + 4 * n) = acc[ai][bj][m][n]; }
; template <class Epi, class Sched, bool ALIGN_EPI = false, bool SP2 = false>
; __device__ __forceinline__ void gemm_phase(PG8_LAS unsigned char* lds, const Gemm g, const Sched& S, const Epi& E) {
;     ...
;     f32x4 acc[2][2][4][2];
; #pragma unroll
;     for (int a = 0; a < 2; ++a)
; #pragma unroll
;         for (int b = 0; b < 2; ++b)
; #pragma unroll
;             for (int m = 0; m < 4; ++m)
; #pragma unroll
;                 for (int n = 0; n < 2; ++n) acc[a][b][m][n] = (f32x4){0.f, 0.f, 0.f, 0.f};
;     bf16x8 At[4][2], B0[2][2], B1[2][2];
;     const char* cA = (const char*)g.A + (size_t)cur.pm * tstepA + (size_t)cur.z * g.azs + (size_t)(cur.k0 >> 6) * kstA; const char* cB = (const char*)g.Bt + (size_t)cur.pn * tstepB + (size_t)cur.z * g.bzs + (size_t)cur.k0 * 2;
;     S.a_ready(cur);
;     if constexpr (SP2) {
;         PG8_STAGE(PG8_SB(0, 0), cB, voffB); PG8_STAGE(PG8_SB(0, 1), cB + hstepB, voffB); PG8_STAGE(PG8_SA(0, 0), cA, voffA); PG8_STAGE(PG8_SA(0, 1), cA + hstepA, voffA);
;         if (wr == 1) PG8_BAR;
;         PG8_WAIT_V(2); PG8_BAR;
;         PG8_STAGE(PG8_SB(1, 0), cB + kstep, voffB); PG8_STAGE(PG8_SA(1, 0), cA + kstA, voffA); PG8_STAGE(PG8_SB(1, 1), cB + hstepB + kstep, voffB);
;         PG8_WAIT_V(6); PG8_BAR;
;     } else {
;         PG8_STAGE(PG8_SB(0, 0), cB, voffB); PG8_STAGE(PG8_SA(0, 0), cA, voffA); PG8_STAGE(PG8_SB(0, 1), cB + hstepB, voffB); PG8_STAGE(PG8_SA(0, 1), cA + hstepA, voffA);
;         if (wr == 1) PG8_BAR;
;         PG8_WAIT_V(4); PG8_BAR;
;         PG8_STAGE(PG8_SB(1, 0), cB + kstep, voffB); PG8_STAGE(PG8_SA(1, 0), cA + kstA, voffA); PG8_STAGE(PG8_SB(1, 1), cB + hstepB + kstep, voffB);
;         PG8_WAIT_V(6); PG8_BAR;
;     }
.LBB0_2730:
	v_lshrrev_b32_e32 v17, 1, v8
	v_readlane_b32 s10, v254, 34
	v_and_b32_e32 v18, 24, v17
	v_readlane_b32 s11, v254, 35
	s_add_u32 s72, s10, 0x140000
	v_and_b32_e32 v15, 15, v8
	v_lshlrev_b32_e32 v17, 1, v18
	v_lshlrev_b32_e32 v8, 2, v8
	s_addc_u32 s73, s11, 0
	v_lshl_or_b32 v16, s4, 6, v15
	v_lshl_or_b32 v15, v15, 6, v17
	s_lshl_b32 s4, s4, 13
	v_and_b32_e32 v8, 32, v8
	v_bitop3_b32 v19, v15, s4, v8 bitop3:0xde
	s_lshl_b32 s4, s5, 5
	s_mov_b64 s[52:53], 0x80
	s_and_b32 s12, s4, 0x60
	s_add_i32 m0, s9, 0x18000
	v_lshl_add_u64 v[6:7], v[6:7], 0, s[52:53]
	s_lshl_b32 s4, s12, 7
	s_waitcnt vmcnt(2)
	s_barrier
	global_load_lds_dwordx4 v[6:7], off
	v_lshl_add_u64 v[4:5], v[4:5], 0, s[52:53]
	s_add_i32 m0, s9, 0x1a000
	s_add_i32 s74, s9, 0x8000
	s_add_i32 s75, s9, 0xa000
	global_load_lds_dwordx4 v[4:5], off
	v_lshl_add_u64 v[0:1], v[0:1], 0, s[52:53]
	s_mov_b32 m0, s74
	s_add_u32 s10, s48, 0x80080
	global_load_lds_dwordx4 v[0:1], off
	v_lshl_add_u64 v[0:1], v[2:3], 0, s[52:53]
	s_mov_b32 m0, s75
	s_addc_u32 s11, s49, 0
	global_load_lds_dwordx4 v[0:1], off
	s_add_i32 m0, s9, 0x1c000
	v_lshl_add_u64 v[0:1], s[10:11], 0, v[146:147]
	global_load_lds_dwordx4 v[0:1], off
	v_lshl_add_u64 v[0:1], s[10:11], 0, v[150:151]
	s_add_i32 m0, s9, 0x1e000
	v_ashrrev_i32_e32 v17, 31, v16
	global_load_lds_dwordx4 v[0:1], off
	v_or_b32_e32 v0, 16, v16
	v_ashrrev_i32_e32 v1, 31, v0
	v_lshlrev_b64 v[154:155], 13, v[0:1]
	v_or_b32_e32 v0, 32, v16
	s_mov_b64 s[0:1], 0x140000
	v_lshlrev_b64 v[152:153], 13, v[16:17]
	v_ashrrev_i32_e32 v1, 31, v0
	v_lshlrev_b64 v[156:157], 13, v[0:1]
	v_or_b32_e32 v0, 48, v16
	v_lshl_add_u64 v[164:165], v[152:153], 0, s[0:1]
	s_mov_b64 s[0:1], 0x160000
	v_ashrrev_i32_e32 v1, 31, v0
	v_lshl_add_u64 v[166:167], v[152:153], 0, s[0:1]
	v_readlane_b32 s0, v255, 12
	v_lshlrev_b64 v[158:159], 13, v[0:1]
	v_lshlrev_b64 v[0:1], 12, v[16:17]
	v_readlane_b32 s1, v255, 13
	v_bitop3_b32 v180, v15, s4, v8 bitop3:0xde
	s_mov_b64 s[4:5], 0x80080
	v_lshl_add_u64 v[168:169], s[0:1], 0, v[0:1]
	v_lshlrev_b32_e32 v0, 15, v9
	v_and_b32_e32 v0, 0xffff0000, v0
	v_lshl_add_u32 v0, v10, 12, v0
	v_and_b32_e32 v1, 1, v9
	v_lshl_or_b32 v0, v1, 6, v0
	v_lshl_add_u32 v0, v11, 1, v0
	v_mov_b32_e32 v1, v147
	v_lshl_add_u64 v[170:171], v[0:1], 0, s[4:5]
	v_lshlrev_b32_e32 v0, 15, v12
	v_and_b32_e32 v0, 0xffff0000, v0
	v_lshl_add_u32 v0, v13, 12, v0
	v_and_b32_e32 v1, 1, v12
	s_waitcnt vmcnt(6)
	s_mov_b64 s[10:11], 0x100000
	v_lshl_or_b32 v0, v1, 6, v0
	s_cmpk_lt_u32 s3, 0x100
	v_lshl_add_u64 v[160:161], v[152:153], 0, s[10:11]
	s_mov_b64 s[10:11], 0x120000
	v_lshl_add_u32 v0, v14, 1, v0
	v_mov_b32_e32 v1, v147
	s_mov_b32 s76, 0
	s_cselect_b64 s[54:55], -1, 0
	v_lshl_add_u64 v[162:163], v[152:153], 0, s[10:11]
	v_or_b32_e32 v181, s12, v18
	v_lshl_add_u64 v[172:173], v[0:1], 0, s[4:5]
	s_add_i32 s77, 0, 0x10000
	s_add_i32 s84, 0, 0x14000
	v_add_u32_e32 v182, 0, v19
	s_mov_b64 s[34:35], 0x100
	v_mov_b64_e32 v[174:175], 0x1ff
	v_mov_b32_e32 v0, v147
	v_mov_b64_e32 v[2:3], 0
	v_mov_b64_e32 v[4:5], 0
	v_mov_b64_e32 v[6:7], 0
	v_mov_b64_e32 v[8:9], 0
	v_mov_b64_e32 v[10:11], 0
	v_mov_b64_e32 v[12:13], 0
	v_mov_b64_e32 v[14:15], 0
	v_mov_b64_e32 v[16:17], 0
	v_mov_b64_e32 v[18:19], 0
	v_mov_b64_e32 v[20:21], 0
	v_mov_b64_e32 v[22:23], 0
	v_mov_b64_e32 v[24:25], 0
	v_mov_b64_e32 v[26:27], 0
	v_mov_b64_e32 v[28:29], 0
	v_mov_b64_e32 v[30:31], 0
	v_mov_b64_e32 v[32:33], 0
	v_mov_b64_e32 v[34:35], 0
	v_mov_b64_e32 v[36:37], 0
	v_mov_b64_e32 v[38:39], 0
	v_mov_b64_e32 v[40:41], 0
	v_mov_b64_e32 v[42:43], 0
	v_mov_b64_e32 v[44:45], 0
	v_mov_b64_e32 v[46:47], 0
	v_mov_b64_e32 v[48:49], 0
	v_mov_b64_e32 v[50:51], 0
	v_mov_b64_e32 v[52:53], 0
	v_mov_b64_e32 v[54:55], 0
	v_mov_b64_e32 v[56:57], 0
	v_mov_b64_e32 v[58:59], 0
	v_mov_b64_e32 v[60:61], 0
	v_mov_b64_e32 v[62:63], 0
	v_mov_b64_e32 v[64:65], 0
	v_mov_b64_e32 v[66:67], 0
	v_mov_b64_e32 v[68:69], 0
	v_mov_b64_e32 v[70:71], 0
	v_mov_b64_e32 v[72:73], 0
	v_mov_b64_e32 v[74:75], 0
	v_mov_b64_e32 v[76:77], 0
	v_mov_b64_e32 v[78:79], 0
	v_mov_b64_e32 v[80:81], 0
	v_mov_b64_e32 v[82:83], 0
	v_mov_b64_e32 v[84:85], 0
	v_mov_b64_e32 v[86:87], 0
	v_mov_b64_e32 v[88:89], 0
	v_mov_b64_e32 v[90:91], 0
	v_mov_b64_e32 v[92:93], 0
	v_mov_b64_e32 v[94:95], 0
	v_mov_b64_e32 v[96:97], 0
	v_mov_b64_e32 v[98:99], 0
	v_mov_b64_e32 v[100:101], 0
	v_mov_b64_e32 v[102:103], 0
	v_mov_b64_e32 v[104:105], 0
	v_mov_b64_e32 v[106:107], 0
	v_mov_b64_e32 v[108:109], 0
	v_mov_b64_e32 v[110:111], 0
	v_mov_b64_e32 v[112:113], 0
	v_mov_b64_e32 v[114:115], 0
	v_mov_b64_e32 v[116:117], 0
	v_mov_b64_e32 v[118:119], 0
	v_mov_b64_e32 v[120:121], 0
	v_mov_b64_e32 v[122:123], 0
	v_mov_b64_e32 v[124:125], 0
	v_mov_b64_e32 v[126:127], 0
	v_readlane_b32 s14, v254, 54
	s_barrier
	s_branch .LBB0_2733
.LBB0_2731:
	v_mov_b32_e32 v0, 0
	s_mov_b32 s7, s11
	s_mov_b32 s44, s10
	s_mov_b32 s36, s0
	s_mov_b32 s42, s20
	s_mov_b64 s[48:49], s[60:61]
	s_mov_b64 s[46:47], s[58:59]
	s_mov_b32 s76, s3
	v_mov_b32_e32 v1, v0
	v_mov_b64_e32 v[2:3], 0
	v_mov_b64_e32 v[4:5], 0
	v_mov_b64_e32 v[6:7], 0
	v_mov_b64_e32 v[8:9], 0
	v_mov_b64_e32 v[10:11], 0
	v_mov_b64_e32 v[12:13], 0
	v_mov_b64_e32 v[14:15], 0
	v_mov_b64_e32 v[16:17], 0
	v_mov_b64_e32 v[18:19], 0
	v_mov_b64_e32 v[20:21], 0
	v_mov_b64_e32 v[22:23], 0
	v_mov_b64_e32 v[24:25], 0
	v_mov_b64_e32 v[26:27], 0
	v_mov_b64_e32 v[28:29], 0
	v_mov_b64_e32 v[30:31], 0
	v_mov_b64_e32 v[32:33], 0
	v_mov_b64_e32 v[34:35], 0
	v_mov_b64_e32 v[36:37], 0
	v_mov_b64_e32 v[38:39], 0
	v_mov_b64_e32 v[40:41], 0
	v_mov_b64_e32 v[42:43], 0
	v_mov_b64_e32 v[44:45], 0
	v_mov_b64_e32 v[46:47], 0
	v_mov_b64_e32 v[48:49], 0
	v_mov_b64_e32 v[50:51], 0
	v_mov_b64_e32 v[52:53], 0
	v_mov_b64_e32 v[54:55], 0
	v_mov_b64_e32 v[56:57], 0
	v_mov_b64_e32 v[58:59], 0
	v_mov_b64_e32 v[60:61], 0
	v_mov_b64_e32 v[62:63], 0
	v_mov_b64_e32 v[64:65], 0
	v_mov_b64_e32 v[66:67], 0
	v_mov_b64_e32 v[68:69], 0
	v_mov_b64_e32 v[70:71], 0
	v_mov_b64_e32 v[72:73], 0
	v_mov_b64_e32 v[74:75], 0
	v_mov_b64_e32 v[76:77], 0
	v_mov_b64_e32 v[78:79], 0
	v_mov_b64_e32 v[80:81], 0
	v_mov_b64_e32 v[82:83], 0
	v_mov_b64_e32 v[84:85], 0
	v_mov_b64_e32 v[86:87], 0
	v_mov_b64_e32 v[88:89], 0
	v_mov_b64_e32 v[90:91], 0
	v_mov_b64_e32 v[92:93], 0
	v_mov_b64_e32 v[94:95], 0
	v_mov_b64_e32 v[96:97], 0
	v_mov_b64_e32 v[98:99], 0
	v_mov_b64_e32 v[100:101], 0
	v_mov_b64_e32 v[102:103], 0
	v_mov_b64_e32 v[104:105], 0
	v_mov_b64_e32 v[106:107], 0
	v_mov_b64_e32 v[108:109], 0
	v_mov_b64_e32 v[110:111], 0
	v_mov_b64_e32 v[112:113], 0
	v_mov_b64_e32 v[114:115], 0
	v_mov_b64_e32 v[116:117], 0
	v_mov_b64_e32 v[118:119], 0
	v_mov_b64_e32 v[120:121], 0
	v_mov_b64_e32 v[122:123], 0
	v_mov_b64_e32 v[124:125], 0
	v_mov_b64_e32 v[126:127], 0

; template <class Epi, class Sched, bool ALIGN_EPI = false, bool SP2 = false>
; __device__ __forceinline__ void gemm_phase(PG8_LAS unsigned char* lds, const Gemm g, const Sched& S, const Epi& E) {
;     ...
;         const char* nA = has_next ? (const char*)g.A + (size_t)nxt.pm * tstepA + (size_t)nxt.z * g.azs + (size_t)(nxt.k0 >> 6) * kstA : cA; const char* nB = has_next ? (const char*)g.Bt + (size_t)nxt.pn * tstepB + (size_t)nxt.z * g.bzs + (size_t)nxt.k0 * 2 : cB;
;     ...
; #pragma unroll
;         for (int a = 0; a < 2; ++a)
; #pragma unroll
;             for (int b = 0; b < 2; ++b)
; #pragma unroll
;                 for (int m = 0; m < 4; ++m)
; #pragma unroll
;                     for (int n = 0; n < 2; ++n) acc[a][b][m][n] = (f32x4){0.f, 0.f, 0.f, 0.f};
;         cur = nxt; cA = nA; cB = nB; ++ui;
.LBB0_3057:
	s_ashr_i32 s23, s22, 31
	s_lshl_b64 s[4:5], s[22:23], 20
	v_readlane_b32 s12, v254, 41
	v_readlane_b32 s13, v254, 42
	s_add_u32 s24, s12, s4
	s_addc_u32 s25, s13, s5
	s_and_b64 s[4:5], s[36:37], exec
	s_cselect_b32 s4, s25, s41
	s_cselect_b32 s5, s24, s40
	s_ashr_i32 s21, s20, 31
	s_lshl_b64 s[12:13], s[20:21], 20
	s_add_u32 s30, s3, s12
	s_addc_u32 s31, s6, s13
	s_and_b64 s[12:13], s[36:37], exec
	s_cselect_b32 s12, s31, s43
	s_cselect_b32 s13, s30, s42
	s_add_u32 s40, s40, 0x80080
	s_addc_u32 s41, s41, 0
	s_add_u32 s21, s42, 0x100
	v_mov_b32_e32 v0, 0
	s_addc_u32 s23, s43, 0
	s_mov_b32 s35, -2
	v_mov_b32_e32 v1, v0
	v_mov_b64_e32 v[2:3], 0
	v_mov_b64_e32 v[4:5], 0
	v_mov_b64_e32 v[6:7], 0
	v_mov_b64_e32 v[16:17], 0
	v_mov_b64_e32 v[18:19], 0
	v_mov_b64_e32 v[20:21], 0
	v_mov_b64_e32 v[22:23], 0
	v_mov_b64_e32 v[32:33], 0
	v_mov_b64_e32 v[34:35], 0
	v_mov_b64_e32 v[36:37], 0
	v_mov_b64_e32 v[38:39], 0
	v_mov_b64_e32 v[48:49], 0
	v_mov_b64_e32 v[50:51], 0
	v_mov_b64_e32 v[52:53], 0
	v_mov_b64_e32 v[54:55], 0
	v_mov_b64_e32 v[8:9], 0
	v_mov_b64_e32 v[10:11], 0
	v_mov_b64_e32 v[12:13], 0
	v_mov_b64_e32 v[14:15], 0
	v_mov_b64_e32 v[24:25], 0
	v_mov_b64_e32 v[26:27], 0
	v_mov_b64_e32 v[28:29], 0
	v_mov_b64_e32 v[30:31], 0
	v_mov_b64_e32 v[40:41], 0
	v_mov_b64_e32 v[42:43], 0
	v_mov_b64_e32 v[44:45], 0
	v_mov_b64_e32 v[46:47], 0
	v_mov_b64_e32 v[56:57], 0
	v_mov_b64_e32 v[58:59], 0
	v_mov_b64_e32 v[60:61], 0
	v_mov_b64_e32 v[62:63], 0
	v_mov_b64_e32 v[64:65], 0
	v_mov_b64_e32 v[66:67], 0
	v_mov_b64_e32 v[68:69], 0
	v_mov_b64_e32 v[70:71], 0
	v_mov_b64_e32 v[80:81], 0
	v_mov_b64_e32 v[82:83], 0
	v_mov_b64_e32 v[84:85], 0
	v_mov_b64_e32 v[86:87], 0
	v_mov_b64_e32 v[96:97], 0
	v_mov_b64_e32 v[98:99], 0
	v_mov_b64_e32 v[100:101], 0
	v_mov_b64_e32 v[102:103], 0
	v_mov_b64_e32 v[112:113], 0
	v_mov_b64_e32 v[114:115], 0
	v_mov_b64_e32 v[116:117], 0
	v_mov_b64_e32 v[118:119], 0
	v_mov_b64_e32 v[72:73], 0
	v_mov_b64_e32 v[74:75], 0
	v_mov_b64_e32 v[76:77], 0
	v_mov_b64_e32 v[78:79], 0
	v_mov_b64_e32 v[88:89], 0
	v_mov_b64_e32 v[90:91], 0
	v_mov_b64_e32 v[92:93], 0
	v_mov_b64_e32 v[94:95], 0
	v_mov_b64_e32 v[104:105], 0
	v_mov_b64_e32 v[106:107], 0
	v_mov_b64_e32 v[108:109], 0
	v_mov_b64_e32 v[110:111], 0
	v_mov_b64_e32 v[120:121], 0
	v_mov_b64_e32 v[122:123], 0
	v_mov_b64_e32 v[124:125], 0
	v_mov_b64_e32 v[126:127], 0

;     __device__ __forceinline__ void operator()(const f32x4 (&acc)[2][2][4][2], const Unit& u, int wr, int wc, int fr, int fq) const {
;     ...
;         const int rloc0 = wr * 64 + fr, col0 = u.pn * BM + wc * 32 + 8 * fq;
;         if (u.z) {
;             float* sp = SLAB + ((size_t)(u.z - 1) * 512 + b * 256) * 2048;
; #pragma unroll
;             for (int ai = 0; ai < 2; ++ai)
; #pragma unroll
;                 for (int m = 0; m < 4; ++m) { float* dp = sp + (size_t)(rloc0 + ai * HALF + m * 16) * 2048 + col0;
; #pragma unroll
;                     for (int bj = 0; bj < 2; ++bj)
; #pragma unroll
;                         for (int n = 0; n < 2; ++n) *(f32x4*)(dp + bj * HALF + 4 * n) = acc[ai][bj][m][n]; }
; template <class Epi, class Sched, bool ALIGN_EPI = false, bool SP2 = false>
; __device__ __forceinline__ void gemm_phase(PG8_LAS unsigned char* lds, const Gemm g, const Sched& S, const Epi& E) {
;     ...
;     f32x4 acc[2][2][4][2];
; #pragma unroll
;     for (int a = 0; a < 2; ++a)
; #pragma unroll
;         for (int b = 0; b < 2; ++b)
; #pragma unroll
;             for (int m = 0; m < 4; ++m)
; #pragma unroll
;                 for (int n = 0; n < 2; ++n) acc[a][b][m][n] = (f32x4){0.f, 0.f, 0.f, 0.f};
;     bf16x8 At[4][2], B0[2][2], B1[2][2];
;     const char* cA = (const char*)g.A + (size_t)cur.pm * tstepA + (size_t)cur.z * g.azs + (size_t)(cur.k0 >> 6) * kstA; const char* cB = (const char*)g.Bt + (size_t)cur.pn * tstepB + (size_t)cur.z * g.bzs + (size_t)cur.k0 * 2;
;     S.a_ready(cur);
;     if constexpr (SP2) {
;         PG8_STAGE(PG8_SB(0, 0), cB, voffB); PG8_STAGE(PG8_SB(0, 1), cB + hstepB, voffB); PG8_STAGE(PG8_SA(0, 0), cA, voffA); PG8_STAGE(PG8_SA(0, 1), cA + hstepA, voffA);
;         if (wr == 1) PG8_BAR;
;         PG8_WAIT_V(2); PG8_BAR;
;         PG8_STAGE(PG8_SB(1, 0), cB + kstep, voffB); PG8_STAGE(PG8_SA(1, 0), cA + kstA, voffA); PG8_STAGE(PG8_SB(1, 1), cB + hstepB + kstep, voffB);
;         PG8_WAIT_V(6); PG8_BAR;
;     } else {
;         PG8_STAGE(PG8_SB(0, 0), cB, voffB); PG8_STAGE(PG8_SA(0, 0), cA, voffA); PG8_STAGE(PG8_SB(0, 1), cB + hstepB, voffB); PG8_STAGE(PG8_SA(0, 1), cA + hstepA, voffA);
;         if (wr == 1) PG8_BAR;
;         PG8_WAIT_V(4); PG8_BAR;
;         PG8_STAGE(PG8_SB(1, 0), cB + kstep, voffB); PG8_STAGE(PG8_SA(1, 0), cA + kstA, voffA); PG8_STAGE(PG8_SB(1, 1), cB + hstepB + kstep, voffB);
;         PG8_WAIT_V(6); PG8_BAR;
;     }
.LBB0_3128:
	v_lshrrev_b32_e32 v13, 1, v4
	v_and_b32_e32 v14, 24, v13
	s_add_u32 s60, s14, 0x146000
	v_and_b32_e32 v11, 15, v4
	v_lshlrev_b32_e32 v13, 1, v14
	v_lshlrev_b32_e32 v4, 2, v4
	s_addc_u32 s61, s15, 0
	v_lshl_or_b32 v12, s5, 6, v11
	v_lshl_or_b32 v11, v11, 6, v13
	s_lshl_b32 s0, s5, 13
	v_and_b32_e32 v4, 32, v4
	v_bitop3_b32 v15, v11, s0, v4 bitop3:0xde
	s_lshl_b32 s0, s10, 5
	s_mov_b64 s[30:31], 0x80
	s_and_b32 s5, s0, 0x60
	s_add_i32 m0, s55, 0x18000
	v_lshl_add_u64 v[2:3], v[2:3], 0, s[30:31]
	s_lshl_b32 s0, s5, 7
	s_waitcnt vmcnt(2)
	s_barrier
	global_load_lds_dwordx4 v[2:3], off
	s_add_i32 m0, s55, 0x1a000
	v_bitop3_b32 v178, v11, s0, v4 bitop3:0xde
	s_add_u32 s0, s20, 0x8000
	v_lshl_add_u64 v[0:1], v[0:1], 0, s[30:31]
	s_addc_u32 s1, s21, 0
	s_add_i32 s62, s55, 0x8000
	global_load_lds_dwordx4 v[0:1], off
	v_lshl_add_u64 v[0:1], s[0:1], 0, v[128:129]
	s_mov_b32 m0, s62
	s_add_i32 s63, s55, 0xa000
	global_load_lds_dwordx4 v[0:1], off
	v_lshl_add_u64 v[0:1], s[0:1], 0, v[132:133]
	s_add_u32 s0, s22, 0x160080
	s_mov_b32 m0, s63
	s_addc_u32 s1, s23, 0
	global_load_lds_dwordx4 v[0:1], off
	s_add_i32 m0, s55, 0x1c000
	v_lshl_add_u64 v[0:1], s[0:1], 0, v[130:131]
	global_load_lds_dwordx4 v[0:1], off
	v_lshl_add_u64 v[0:1], s[0:1], 0, v[134:135]
	s_add_i32 m0, s55, 0x1e000
	v_ashrrev_i32_e32 v13, 31, v12
	global_load_lds_dwordx4 v[0:1], off
	v_or_b32_e32 v0, 16, v12
	v_lshlrev_b64 v[136:137], 13, v[12:13]
	v_ashrrev_i32_e32 v1, 31, v0
	s_mov_b64 s[0:1], 0x100000
	v_lshlrev_b64 v[138:139], 13, v[0:1]
	v_or_b32_e32 v0, 32, v12
	v_lshl_add_u64 v[144:145], v[136:137], 0, s[0:1]
	s_mov_b64 s[0:1], 0x120000
	v_ashrrev_i32_e32 v1, 31, v0
	v_lshl_add_u64 v[146:147], v[136:137], 0, s[0:1]
	s_mov_b64 s[0:1], 0x140000
	v_lshlrev_b64 v[140:141], 13, v[0:1]
	v_or_b32_e32 v0, 48, v12
	v_lshl_add_u64 v[148:149], v[136:137], 0, s[0:1]
	s_mov_b64 s[0:1], 0x160000
	v_ashrrev_i32_e32 v1, 31, v0
	v_lshl_add_u64 v[150:151], v[136:137], 0, s[0:1]
	v_readlane_b32 s0, v255, 12
	v_lshlrev_b64 v[142:143], 13, v[0:1]
	v_lshlrev_b64 v[0:1], 12, v[12:13]
	v_readlane_b32 s1, v255, 13
	s_waitcnt vmcnt(6)
	s_cmpk_lt_u32 s4, 0x100
	s_cselect_b64 s[36:37], -1, 0
	v_lshl_add_u64 v[152:153], s[0:1], 0, v[0:1]
	v_lshlrev_b32_e32 v0, 10, v5
	v_and_b32_e32 v0, 0xfffff800, v0
	v_lshl_add_u32 v0, v6, 7, v0
	v_and_b32_e32 v1, 1, v5
	v_lshl_or_b32 v0, v1, 6, v0
	v_lshl_add_u32 v0, v7, 1, v0
	v_mov_b32_e32 v1, v131
	s_mov_b64 s[0:1], 0xc000
	v_lshl_add_u64 v[154:155], v[0:1], 0, s[0:1]
	v_lshlrev_b32_e32 v0, 10, v8
	v_and_b32_e32 v0, 0xfffff800, v0
	v_lshl_add_u32 v0, v9, 7, v0
	v_and_b32_e32 v1, 1, v8
	v_lshl_or_b32 v0, v1, 6, v0
	v_lshl_add_u32 v0, v10, 1, v0
	v_mov_b32_e32 v1, v131
	v_or_b32_e32 v179, s5, v14
	v_lshl_add_u64 v[156:157], v[0:1], 0, s[0:1]
	s_add_i32 s64, 0, 0x10000
	s_add_i32 s65, 0, 0x14000
	v_add_u32_e32 v180, 0, v15
	s_mov_b64 s[38:39], 0x10000
	v_mov_b64_e32 v[158:159], 0x1ff
	v_mov_b32_e32 v0, v131
	v_mov_b64_e32 v[2:3], 0
	v_mov_b64_e32 v[4:5], 0
	v_mov_b64_e32 v[6:7], 0
	v_mov_b64_e32 v[8:9], 0
	v_mov_b64_e32 v[10:11], 0
	v_mov_b64_e32 v[12:13], 0
	v_mov_b64_e32 v[14:15], 0
	v_mov_b64_e32 v[16:17], 0
	v_mov_b64_e32 v[18:19], 0
	v_mov_b64_e32 v[20:21], 0
	v_mov_b64_e32 v[22:23], 0
	v_mov_b64_e32 v[24:25], 0
	v_mov_b64_e32 v[26:27], 0
	v_mov_b64_e32 v[28:29], 0
	v_mov_b64_e32 v[30:31], 0
	v_mov_b64_e32 v[32:33], 0
	v_mov_b64_e32 v[34:35], 0
	v_mov_b64_e32 v[36:37], 0
	v_mov_b64_e32 v[38:39], 0
	v_mov_b64_e32 v[40:41], 0
	v_mov_b64_e32 v[42:43], 0
	v_mov_b64_e32 v[44:45], 0
	v_mov_b64_e32 v[46:47], 0
	v_mov_b64_e32 v[48:49], 0
	v_mov_b64_e32 v[50:51], 0
	v_mov_b64_e32 v[52:53], 0
	v_mov_b64_e32 v[54:55], 0
	v_mov_b64_e32 v[56:57], 0
	v_mov_b64_e32 v[58:59], 0
	v_mov_b64_e32 v[60:61], 0
	v_mov_b64_e32 v[62:63], 0
	v_mov_b64_e32 v[64:65], 0
	v_mov_b64_e32 v[66:67], 0
	v_mov_b64_e32 v[68:69], 0
	v_mov_b64_e32 v[70:71], 0
	v_mov_b64_e32 v[72:73], 0
	v_mov_b64_e32 v[74:75], 0
	v_mov_b64_e32 v[76:77], 0
	v_mov_b64_e32 v[78:79], 0
	v_mov_b64_e32 v[80:81], 0
	v_mov_b64_e32 v[82:83], 0
	v_mov_b64_e32 v[84:85], 0
	v_mov_b64_e32 v[86:87], 0
	v_mov_b64_e32 v[88:89], 0
	v_mov_b64_e32 v[90:91], 0
	v_mov_b64_e32 v[92:93], 0
	v_mov_b64_e32 v[94:95], 0
	v_mov_b64_e32 v[96:97], 0
	v_mov_b64_e32 v[98:99], 0
	v_mov_b64_e32 v[100:101], 0
	v_mov_b64_e32 v[102:103], 0
	v_mov_b64_e32 v[104:105], 0
	v_mov_b64_e32 v[106:107], 0
	v_mov_b64_e32 v[108:109], 0
	v_mov_b64_e32 v[110:111], 0
	v_mov_b64_e32 v[112:113], 0
	v_mov_b64_e32 v[114:115], 0
	v_mov_b64_e32 v[116:117], 0
	v_mov_b64_e32 v[118:119], 0
	v_mov_b64_e32 v[120:121], 0
	v_mov_b64_e32 v[122:123], 0
	v_mov_b64_e32 v[124:125], 0
	v_mov_b64_e32 v[126:127], 0
	v_readlane_b32 s14, v254, 54
	s_barrier
	s_branch .LBB0_3131
.LBB0_3129:
	v_mov_b32_e32 v0, 0
	s_mov_b32 s7, s69
	s_mov_b32 s18, s11
	s_mov_b32 s6, s66
	s_mov_b32 s16, s67
	s_mov_b64 s[22:23], s[44:45]
	s_mov_b64 s[20:21], s[42:43]
	s_mov_b32 s59, s10
	v_mov_b32_e32 v1, v0
	v_mov_b64_e32 v[2:3], 0
	v_mov_b64_e32 v[4:5], 0
	v_mov_b64_e32 v[6:7], 0
	v_mov_b64_e32 v[8:9], 0
	v_mov_b64_e32 v[10:11], 0
	v_mov_b64_e32 v[12:13], 0
	v_mov_b64_e32 v[14:15], 0
	v_mov_b64_e32 v[16:17], 0
	v_mov_b64_e32 v[18:19], 0
	v_mov_b64_e32 v[20:21], 0
	v_mov_b64_e32 v[22:23], 0
	v_mov_b64_e32 v[24:25], 0
	v_mov_b64_e32 v[26:27], 0
	v_mov_b64_e32 v[28:29], 0
	v_mov_b64_e32 v[30:31], 0
	v_mov_b64_e32 v[32:33], 0
	v_mov_b64_e32 v[34:35], 0
	v_mov_b64_e32 v[36:37], 0
	v_mov_b64_e32 v[38:39], 0
	v_mov_b64_e32 v[40:41], 0
	v_mov_b64_e32 v[42:43], 0
	v_mov_b64_e32 v[44:45], 0
	v_mov_b64_e32 v[46:47], 0
	v_mov_b64_e32 v[48:49], 0
	v_mov_b64_e32 v[50:51], 0
	v_mov_b64_e32 v[52:53], 0
	v_mov_b64_e32 v[54:55], 0
	v_mov_b64_e32 v[56:57], 0
	v_mov_b64_e32 v[58:59], 0
	v_mov_b64_e32 v[60:61], 0
	v_mov_b64_e32 v[62:63], 0
	v_mov_b64_e32 v[64:65], 0
	v_mov_b64_e32 v[66:67], 0
	v_mov_b64_e32 v[68:69], 0
	v_mov_b64_e32 v[70:71], 0
	v_mov_b64_e32 v[72:73], 0
	v_mov_b64_e32 v[74:75], 0
	v_mov_b64_e32 v[76:77], 0
	v_mov_b64_e32 v[78:79], 0
	v_mov_b64_e32 v[80:81], 0
	v_mov_b64_e32 v[82:83], 0
	v_mov_b64_e32 v[84:85], 0
	v_mov_b64_e32 v[86:87], 0
	v_mov_b64_e32 v[88:89], 0
	v_mov_b64_e32 v[90:91], 0
	v_mov_b64_e32 v[92:93], 0
	v_mov_b64_e32 v[94:95], 0
	v_mov_b64_e32 v[96:97], 0
	v_mov_b64_e32 v[98:99], 0
	v_mov_b64_e32 v[100:101], 0
	v_mov_b64_e32 v[102:103], 0
	v_mov_b64_e32 v[104:105], 0
	v_mov_b64_e32 v[106:107], 0
	v_mov_b64_e32 v[108:109], 0
	v_mov_b64_e32 v[110:111], 0
	v_mov_b64_e32 v[112:113], 0
	v_mov_b64_e32 v[114:115], 0
	v_mov_b64_e32 v[116:117], 0
	v_mov_b64_e32 v[118:119], 0
	v_mov_b64_e32 v[120:121], 0
	v_mov_b64_e32 v[122:123], 0
	v_mov_b64_e32 v[124:125], 0
	v_mov_b64_e32 v[126:127], 0
